# GEMM K-loops: inverted priority policy - s_setprio 1 during the ds_read/DMA load segment, 0 during the MFMA block; on top of v42
# baseline (speedup 1.0000x reference)
; #define PG8_STAGE(bufoff, gbase, voff) do { _Pragma("unroll") for (int _i = 0; _i < 2; ++_i) \
;         __builtin_amdgcn_global_load_lds((const unsigned*)((const char*)(gbase) + (voff)[_i]), (LAS unsigned*)(lds + (bufoff) + ldsw + _i * 8192), 16, 0, 0); } while (0)
; #define PG8_LDA(dst, b, h) do { _Pragma("unroll") for (int m = 0; m < 4; ++m) _Pragma("unroll") for (int k = 0; k < 2; ++k) dst[m][k] = *(const LAS bf16x8*)(lds + PG8_SA(b, h) + aoff + m * 2048 + k * 1024); } while (0)
; #define PG8_LDB(dst, b, h) do { _Pragma("unroll") for (int n = 0; n < 2; ++n) _Pragma("unroll") for (int k = 0; k < 2; ++k) dst[n][k] = *(const LAS bf16x8*)(lds + PG8_SB(b, h) + boff + n * 2048 + k * 1024); } while (0)
; #define PG8_MMA(ai, bj, At, Bt) do { __builtin_amdgcn_s_setprio(1); _Pragma("unroll") for (int m = 0; m < 4; ++m) _Pragma("unroll") for (int n = 0; n < 2; ++n) _Pragma("unroll") for (int k = 0; k < 2; ++k) \
;         acc[ai][bj][m][n] = __builtin_amdgcn_mfma_f32_16x16x32_bf16(Bt[n][k], At[m][k], acc[ai][bj][m][n], 0, 0, 0); __builtin_amdgcn_s_setprio(0); } while (0)
; #define PG8_WAIT_V(n) asm volatile("s_waitcnt vmcnt(" #n ")" ::: "memory")
; #define PG8_WAIT_L(n) asm volatile("s_waitcnt lgkmcnt(" #n ")" ::: "memory")
; #define PG8_BAR __builtin_amdgcn_s_barrier()
; #define PG8_SCHED __builtin_amdgcn_sched_barrier(0)
; template <class Epi, class Sched>
; DI void gemm_phase(LAS unsigned char* lds, const int wv, const int lda, const int ldb, const Sched& S, const Epi& E) {
;     ...
;             const bool last = (t == nt - 2);
;             const char* a1 = cA + (size_t)(t + 1) * kstep;
;             const char* a2 = last ? nA : cA + (size_t)(t + 2) * kstep; const char* b2 = last ? nB : cB + (size_t)(t + 2) * kstep;
;             const char* a3 = a2 + kstep; const char* b3 = b2 + kstep;
;             PG8_LDB(B0, 0, 0); PG8_LDB(B1, 0, 1); PG8_SCHED; PG8_LDA(At, 0, 0); PG8_STAGE(PG8_SA(1, 1), a1 + hstepA, voffA);
;             PG8_WAIT_V(8); PG8_WAIT_L(0); PG8_BAR; PG8_MMA(0, 0, At, B0); PG8_MMA(0, 1, At, B1); PG8_BAR; PG8_SCHED;
;             PG8_LDA(At, 0, 1); PG8_STAGE(PG8_SB(0, 0), b2, voffB); PG8_STAGE(PG8_SB(0, 1), b2 + hstepB, voffB); PG8_STAGE(PG8_SA(0, 0), a2, voffA);
;             PG8_WAIT_V(8); PG8_WAIT_L(0); PG8_BAR; PG8_MMA(1, 0, At, B0); PG8_MMA(1, 1, At, B1); PG8_BAR; PG8_SCHED;
.LBB0_378:
	s_add_u32 s33, s34, 0xfff80080
	s_addc_u32 s36, s35, -1
	s_add_i32 s61, 0, 0x10000
	s_cmp_eq_u32 s23, 28
	s_cselect_b32 s39, s0, s36
	s_cselect_b32 s38, s1, s33
	s_cselect_b32 s37, s5, s19
	s_cselect_b32 s36, s16, s17
	s_add_i32 s33, 0, 0x14000
	v_add_u32_e32 v154, s61, v170
	v_add_u32_e32 v173, s33, v170
	ds_read_b128 v[104:107], v154
	ds_read_b128 v[108:111], v154 offset:1024
	ds_read_b128 v[150:153], v154 offset:2048
	ds_read_b128 v[154:157], v154 offset:3072
	ds_read_b128 v[158:161], v173
	ds_read_b128 v[162:165], v173 offset:1024
	ds_read_b128 v[166:169], v173 offset:2048
	ds_read_b128 v[174:177], v173 offset:3072
	v_lshl_add_u64 v[182:183], s[34:35], 0, v[146:147]
	s_add_i32 m0, s31, 0xc000
	ds_read_b128 v[178:181], v172
	ds_read_b128 v[200:203], v172 offset:1024
	ds_read_b128 v[204:207], v172 offset:2048
	ds_read_b128 v[208:211], v172 offset:3072
	ds_read_b128 v[212:215], v172 offset:4096
	ds_read_b128 v[216:219], v172 offset:5120
	ds_read_b128 v[220:223], v172 offset:6144
	ds_read_b128 v[234:237], v172 offset:7168
	global_load_lds_dwordx4 v[182:183], off
	v_lshl_add_u64 v[182:183], s[34:35], 0, v[148:149]
	s_add_i32 m0, s31, 0xe000
	s_nop 0
	global_load_lds_dwordx4 v[182:183], off
	s_waitcnt vmcnt(8)
	s_waitcnt lgkmcnt(0)
	s_barrier
	s_setprio 0
	s_waitcnt lgkmcnt(0)
	v_mfma_f32_16x16x32_bf16 v[132:135], v[104:107], v[178:181], v[132:135]
	v_mfma_f32_16x16x32_bf16 v[128:131], v[150:153], v[178:181], v[128:131]
	v_mfma_f32_16x16x32_bf16 v[124:127], v[104:107], v[204:207], v[124:127]
	v_mfma_f32_16x16x32_bf16 v[120:123], v[150:153], v[204:207], v[120:123]
	v_mfma_f32_16x16x32_bf16 v[116:119], v[104:107], v[212:215], v[116:119]
	v_mfma_f32_16x16x32_bf16 v[112:115], v[150:153], v[212:215], v[112:115]
	v_mfma_f32_16x16x32_bf16 v[100:103], v[104:107], v[220:223], v[100:103]
	v_mfma_f32_16x16x32_bf16 v[96:99], v[150:153], v[220:223], v[96:99]
	v_mfma_f32_16x16x32_bf16 v[132:135], v[108:111], v[200:203], v[132:135]
	v_mfma_f32_16x16x32_bf16 v[128:131], v[154:157], v[200:203], v[128:131]
	v_mfma_f32_16x16x32_bf16 v[124:127], v[108:111], v[208:211], v[124:127]
	v_mfma_f32_16x16x32_bf16 v[120:123], v[154:157], v[208:211], v[120:123]
	v_mfma_f32_16x16x32_bf16 v[116:119], v[108:111], v[216:219], v[116:119]
	v_mfma_f32_16x16x32_bf16 v[112:115], v[154:157], v[216:219], v[112:115]
	v_mfma_f32_16x16x32_bf16 v[100:103], v[108:111], v[234:237], v[100:103]
	v_mfma_f32_16x16x32_bf16 v[96:99], v[154:157], v[234:237], v[96:99]
	v_mfma_f32_16x16x32_bf16 v[60:63], v[158:161], v[178:181], v[60:63]
	v_mfma_f32_16x16x32_bf16 v[56:59], v[166:169], v[178:181], v[56:59]
	v_mfma_f32_16x16x32_bf16 v[52:55], v[158:161], v[204:207], v[52:55]
	v_mfma_f32_16x16x32_bf16 v[48:51], v[166:169], v[204:207], v[48:51]
	v_mfma_f32_16x16x32_bf16 v[44:47], v[158:161], v[212:215], v[44:47]
	v_mfma_f32_16x16x32_bf16 v[40:43], v[166:169], v[212:215], v[40:43]
	v_mfma_f32_16x16x32_bf16 v[36:39], v[158:161], v[220:223], v[36:39]
	v_mfma_f32_16x16x32_bf16 v[32:35], v[166:169], v[220:223], v[32:35]
	v_mfma_f32_16x16x32_bf16 v[60:63], v[162:165], v[200:203], v[60:63]
	v_mfma_f32_16x16x32_bf16 v[56:59], v[174:177], v[200:203], v[56:59]
	v_mfma_f32_16x16x32_bf16 v[52:55], v[162:165], v[208:211], v[52:55]
	v_mfma_f32_16x16x32_bf16 v[48:51], v[174:177], v[208:211], v[48:51]
	v_mfma_f32_16x16x32_bf16 v[44:47], v[162:165], v[216:219], v[44:47]
	v_mfma_f32_16x16x32_bf16 v[40:43], v[174:177], v[216:219], v[40:43]
	v_mfma_f32_16x16x32_bf16 v[36:39], v[162:165], v[234:237], v[36:39]
	v_mfma_f32_16x16x32_bf16 v[32:35], v[174:177], v[234:237], v[32:35]
	s_setprio 1
	s_barrier
	s_add_i32 s61, s61, s47
	v_lshl_add_u64 v[182:183], s[36:37], 0, v[138:139]
	s_mov_b32 m0, s61
	ds_read_b128 v[178:181], v172 offset:16384
	ds_read_b128 v[200:203], v172 offset:17408
	ds_read_b128 v[204:207], v172 offset:18432
	ds_read_b128 v[208:211], v172 offset:19456
	ds_read_b128 v[212:215], v172 offset:20480
	ds_read_b128 v[216:219], v172 offset:21504
	ds_read_b128 v[220:223], v172 offset:22528
	ds_read_b128 v[234:237], v172 offset:23552
	global_load_lds_dwordx4 v[182:183], off
	s_add_i32 m0, s61, 0x2000
	s_add_u32 s62, s36, 0x80000
	v_lshl_add_u64 v[188:189], s[36:37], 0, v[142:143]
	s_addc_u32 s63, s37, 0
	s_add_i32 s33, s33, s47
	global_load_lds_dwordx4 v[188:189], off
	v_lshl_add_u64 v[190:191], s[62:63], 0, v[138:139]
	s_mov_b32 m0, s33
	v_lshl_add_u64 v[196:197], s[38:39], 0, v[140:141]
	global_load_lds_dwordx4 v[190:191], off
	v_lshl_add_u64 v[190:191], s[62:63], 0, v[142:143]
	s_add_i32 m0, s33, 0x2000
	s_nop 0
	global_load_lds_dwordx4 v[190:191], off
	v_lshl_add_u64 v[190:191], s[38:39], 0, v[136:137]
	s_mov_b32 m0, s31
	s_nop 0
	global_load_lds_dwordx4 v[190:191], off
	s_mov_b32 m0, s48
	s_nop 0
	global_load_lds_dwordx4 v[196:197], off
	s_waitcnt vmcnt(8)
	s_waitcnt lgkmcnt(0)
	s_barrier
; #define PG8_STAGE(bufoff, gbase, voff) do { _Pragma("unroll") for (int _i = 0; _i < 2; ++_i) \
;         __builtin_amdgcn_global_load_lds((const unsigned*)((const char*)(gbase) + (voff)[_i]), (LAS unsigned*)(lds + (bufoff) + ldsw + _i * 8192), 16, 0, 0); } while (0)
; #define PG8_LDA(dst, b, h) do { _Pragma("unroll") for (int m = 0; m < 4; ++m) _Pragma("unroll") for (int k = 0; k < 2; ++k) dst[m][k] = *(const LAS bf16x8*)(lds + PG8_SA(b, h) + aoff + m * 2048 + k * 1024); } while (0)
; #define PG8_LDB(dst, b, h) do { _Pragma("unroll") for (int n = 0; n < 2; ++n) _Pragma("unroll") for (int k = 0; k < 2; ++k) dst[n][k] = *(const LAS bf16x8*)(lds + PG8_SB(b, h) + boff + n * 2048 + k * 1024); } while (0)
; #define PG8_MMA(ai, bj, At, Bt) do { __builtin_amdgcn_s_setprio(1); _Pragma("unroll") for (int m = 0; m < 4; ++m) _Pragma("unroll") for (int n = 0; n < 2; ++n) _Pragma("unroll") for (int k = 0; k < 2; ++k) \
;         acc[ai][bj][m][n] = __builtin_amdgcn_mfma_f32_16x16x32_bf16(Bt[n][k], At[m][k], acc[ai][bj][m][n], 0, 0, 0); __builtin_amdgcn_s_setprio(0); } while (0)
; #define PG8_WAIT_V(n) asm volatile("s_waitcnt vmcnt(" #n ")" ::: "memory")
; #define PG8_WAIT_L(n) asm volatile("s_waitcnt lgkmcnt(" #n ")" ::: "memory")
; #define PG8_BAR __builtin_amdgcn_s_barrier()
; #define PG8_SCHED __builtin_amdgcn_sched_barrier(0)
; template <class Epi, class Sched>
; DI void gemm_phase(LAS unsigned char* lds, const int wv, const int lda, const int ldb, const Sched& S, const Epi& E) {
;     ...
;             PG8_WAIT_V(8); PG8_WAIT_L(0); PG8_BAR; PG8_MMA(1, 0, At, B0); PG8_MMA(1, 1, At, B1); PG8_BAR; PG8_SCHED;
;             PG8_LDB(B0, 1, 0); PG8_LDB(B1, 1, 1); PG8_SCHED; PG8_LDA(At, 1, 0); PG8_STAGE(PG8_SA(0, 1), a2 + hstepA, voffA);
;             PG8_WAIT_V(8); PG8_WAIT_L(0); PG8_BAR; PG8_MMA(0, 0, At, B0); PG8_MMA(0, 1, At, B1); PG8_BAR; PG8_SCHED;
	s_setprio 0
	s_waitcnt lgkmcnt(0)
	v_mfma_f32_16x16x32_bf16 v[92:95], v[104:107], v[178:181], v[92:95]
	v_mfma_f32_16x16x32_bf16 v[88:91], v[150:153], v[178:181], v[88:91]
	v_mfma_f32_16x16x32_bf16 v[84:87], v[104:107], v[204:207], v[84:87]
	v_mfma_f32_16x16x32_bf16 v[80:83], v[150:153], v[204:207], v[80:83]
	v_mfma_f32_16x16x32_bf16 v[76:79], v[104:107], v[212:215], v[76:79]
	v_mfma_f32_16x16x32_bf16 v[72:75], v[150:153], v[212:215], v[72:75]
	v_mfma_f32_16x16x32_bf16 v[68:71], v[104:107], v[220:223], v[68:71]
	v_mfma_f32_16x16x32_bf16 v[64:67], v[150:153], v[220:223], v[64:67]
	v_mfma_f32_16x16x32_bf16 v[92:95], v[108:111], v[200:203], v[92:95]
	v_mfma_f32_16x16x32_bf16 v[88:91], v[154:157], v[200:203], v[88:91]
	v_mfma_f32_16x16x32_bf16 v[84:87], v[108:111], v[208:211], v[84:87]
	v_mfma_f32_16x16x32_bf16 v[80:83], v[154:157], v[208:211], v[80:83]
	v_mfma_f32_16x16x32_bf16 v[76:79], v[108:111], v[216:219], v[76:79]
	v_mfma_f32_16x16x32_bf16 v[72:75], v[154:157], v[216:219], v[72:75]
	v_mfma_f32_16x16x32_bf16 v[68:71], v[108:111], v[234:237], v[68:71]
	v_mfma_f32_16x16x32_bf16 v[64:67], v[154:157], v[234:237], v[64:67]
	v_mfma_f32_16x16x32_bf16 v[28:31], v[158:161], v[178:181], v[28:31]
	v_mfma_f32_16x16x32_bf16 v[24:27], v[166:169], v[178:181], v[24:27]
	v_mfma_f32_16x16x32_bf16 v[20:23], v[158:161], v[204:207], v[20:23]
	v_mfma_f32_16x16x32_bf16 v[16:19], v[166:169], v[204:207], v[16:19]
	v_mfma_f32_16x16x32_bf16 v[12:15], v[158:161], v[212:215], v[12:15]
	v_mfma_f32_16x16x32_bf16 v[8:11], v[166:169], v[212:215], v[8:11]
	v_mfma_f32_16x16x32_bf16 v[4:7], v[158:161], v[220:223], v[4:7]
	v_mfma_f32_16x16x32_bf16 v[0:3], v[166:169], v[220:223], v[0:3]
	v_mfma_f32_16x16x32_bf16 v[28:31], v[162:165], v[200:203], v[28:31]
	v_mfma_f32_16x16x32_bf16 v[24:27], v[174:177], v[200:203], v[24:27]
	v_mfma_f32_16x16x32_bf16 v[20:23], v[162:165], v[208:211], v[20:23]
	v_mfma_f32_16x16x32_bf16 v[16:19], v[174:177], v[208:211], v[16:19]
	v_mfma_f32_16x16x32_bf16 v[12:15], v[162:165], v[216:219], v[12:15]
	v_mfma_f32_16x16x32_bf16 v[8:11], v[174:177], v[216:219], v[8:11]
	v_mfma_f32_16x16x32_bf16 v[4:7], v[162:165], v[234:237], v[4:7]
	v_mfma_f32_16x16x32_bf16 v[0:3], v[174:177], v[234:237], v[0:3]
	s_setprio 1
	s_barrier
	s_add_i32 s33, 0, 0x18000
	s_add_i32 s61, 0, 0x1c000
	v_add_u32_e32 v154, s33, v170
	v_add_u32_e32 v173, s61, v170
	ds_read_b128 v[104:107], v154
	ds_read_b128 v[108:111], v154 offset:1024
	ds_read_b128 v[150:153], v154 offset:2048
	ds_read_b128 v[154:157], v154 offset:3072
	ds_read_b128 v[158:161], v173
	ds_read_b128 v[162:165], v173 offset:1024
	ds_read_b128 v[166:169], v173 offset:2048
	ds_read_b128 v[174:177], v173 offset:3072
	s_add_u32 s38, s38, 0x80000
	s_addc_u32 s39, s39, 0
	s_mov_b32 m0, s49
	v_lshl_add_u64 v[198:199], s[38:39], 0, v[136:137]
	ds_read_b128 v[178:181], v172 offset:32768
	ds_read_b128 v[200:203], v172 offset:33792
	ds_read_b128 v[204:207], v172 offset:34816
	ds_read_b128 v[208:211], v172 offset:35840
	ds_read_b128 v[212:215], v172 offset:36864
	ds_read_b128 v[216:219], v172 offset:37888
	ds_read_b128 v[220:223], v172 offset:38912
	ds_read_b128 v[234:237], v172 offset:39936
	global_load_lds_dwordx4 v[198:199], off
	v_lshl_add_u64 v[198:199], s[38:39], 0, v[140:141]
	s_mov_b32 m0, s50
	s_nop 0
	global_load_lds_dwordx4 v[198:199], off
	s_waitcnt vmcnt(8)
	s_waitcnt lgkmcnt(0)
	s_barrier
	s_setprio 0
	s_waitcnt lgkmcnt(0)
	v_mfma_f32_16x16x32_bf16 v[132:135], v[104:107], v[178:181], v[132:135]
	v_mfma_f32_16x16x32_bf16 v[128:131], v[150:153], v[178:181], v[128:131]
	v_mfma_f32_16x16x32_bf16 v[124:127], v[104:107], v[204:207], v[124:127]
	v_mfma_f32_16x16x32_bf16 v[120:123], v[150:153], v[204:207], v[120:123]
	v_mfma_f32_16x16x32_bf16 v[116:119], v[104:107], v[212:215], v[116:119]
	v_mfma_f32_16x16x32_bf16 v[112:115], v[150:153], v[212:215], v[112:115]
	v_mfma_f32_16x16x32_bf16 v[100:103], v[104:107], v[220:223], v[100:103]
	v_mfma_f32_16x16x32_bf16 v[96:99], v[150:153], v[220:223], v[96:99]
	v_mfma_f32_16x16x32_bf16 v[132:135], v[108:111], v[200:203], v[132:135]
	v_mfma_f32_16x16x32_bf16 v[128:131], v[154:157], v[200:203], v[128:131]
	v_mfma_f32_16x16x32_bf16 v[124:127], v[108:111], v[208:211], v[124:127]
	v_mfma_f32_16x16x32_bf16 v[120:123], v[154:157], v[208:211], v[120:123]
	v_mfma_f32_16x16x32_bf16 v[116:119], v[108:111], v[216:219], v[116:119]
	v_mfma_f32_16x16x32_bf16 v[112:115], v[154:157], v[216:219], v[112:115]
	v_mfma_f32_16x16x32_bf16 v[100:103], v[108:111], v[234:237], v[100:103]
	v_mfma_f32_16x16x32_bf16 v[96:99], v[154:157], v[234:237], v[96:99]
	v_mfma_f32_16x16x32_bf16 v[60:63], v[158:161], v[178:181], v[60:63]
	v_mfma_f32_16x16x32_bf16 v[56:59], v[166:169], v[178:181], v[56:59]
	v_mfma_f32_16x16x32_bf16 v[52:55], v[158:161], v[204:207], v[52:55]
	v_mfma_f32_16x16x32_bf16 v[48:51], v[166:169], v[204:207], v[48:51]
	v_mfma_f32_16x16x32_bf16 v[44:47], v[158:161], v[212:215], v[44:47]
	v_mfma_f32_16x16x32_bf16 v[40:43], v[166:169], v[212:215], v[40:43]
	v_mfma_f32_16x16x32_bf16 v[36:39], v[158:161], v[220:223], v[36:39]
	v_mfma_f32_16x16x32_bf16 v[32:35], v[166:169], v[220:223], v[32:35]
	v_mfma_f32_16x16x32_bf16 v[60:63], v[162:165], v[200:203], v[60:63]
	v_mfma_f32_16x16x32_bf16 v[56:59], v[174:177], v[200:203], v[56:59]
	v_mfma_f32_16x16x32_bf16 v[52:55], v[162:165], v[208:211], v[52:55]
	v_mfma_f32_16x16x32_bf16 v[48:51], v[174:177], v[208:211], v[48:51]
	v_mfma_f32_16x16x32_bf16 v[44:47], v[162:165], v[216:219], v[44:47]
	v_mfma_f32_16x16x32_bf16 v[40:43], v[174:177], v[216:219], v[40:43]
	v_mfma_f32_16x16x32_bf16 v[36:39], v[162:165], v[234:237], v[36:39]
	v_mfma_f32_16x16x32_bf16 v[32:35], v[174:177], v[234:237], v[32:35]
	s_setprio 1
	s_barrier
; #define PG8_STAGE(bufoff, gbase, voff) do { _Pragma("unroll") for (int _i = 0; _i < 2; ++_i) \
;         __builtin_amdgcn_global_load_lds((const unsigned*)((const char*)(gbase) + (voff)[_i]), (LAS unsigned*)(lds + (bufoff) + ldsw + _i * 8192), 16, 0, 0); } while (0)
; #define PG8_LDA(dst, b, h) do { _Pragma("unroll") for (int m = 0; m < 4; ++m) _Pragma("unroll") for (int k = 0; k < 2; ++k) dst[m][k] = *(const LAS bf16x8*)(lds + PG8_SA(b, h) + aoff + m * 2048 + k * 1024); } while (0)
; #define PG8_MMA(ai, bj, At, Bt) do { __builtin_amdgcn_s_setprio(1); _Pragma("unroll") for (int m = 0; m < 4; ++m) _Pragma("unroll") for (int n = 0; n < 2; ++n) _Pragma("unroll") for (int k = 0; k < 2; ++k) \
;         acc[ai][bj][m][n] = __builtin_amdgcn_mfma_f32_16x16x32_bf16(Bt[n][k], At[m][k], acc[ai][bj][m][n], 0, 0, 0); __builtin_amdgcn_s_setprio(0); } while (0)
; #define PG8_WAIT_V(n) asm volatile("s_waitcnt vmcnt(" #n ")" ::: "memory")
; #define PG8_WAIT_L(n) asm volatile("s_waitcnt lgkmcnt(" #n ")" ::: "memory")
; #define PG8_BAR __builtin_amdgcn_s_barrier()
; #define PG8_SCHED __builtin_amdgcn_sched_barrier(0)
; template <class Epi, class Sched>
; DI void gemm_phase(LAS unsigned char* lds, const int wv, const int lda, const int ldb, const Sched& S, const Epi& E) {
;     ...
;             PG8_LDA(At, 1, 1); PG8_STAGE(PG8_SB(1, 0), b3, voffB); PG8_STAGE(PG8_SB(1, 1), b3 + hstepB, voffB); PG8_STAGE(PG8_SA(1, 0), a3, voffA);
;             PG8_WAIT_V(8); PG8_WAIT_L(0); PG8_BAR; PG8_MMA(1, 0, At, B0); PG8_MMA(1, 1, At, B1); PG8_BAR; PG8_SCHED;
;         }
;         if (wr == 0) PG8_BAR;
	s_add_i32 s33, s33, s47
	v_lshl_add_u64 v[182:183], v[182:183], 0, s[28:29]
	s_mov_b32 m0, s33
	ds_read_b128 v[178:181], v172 offset:49152
	ds_read_b128 v[200:203], v172 offset:50176
	ds_read_b128 v[204:207], v172 offset:51200
	ds_read_b128 v[208:211], v172 offset:52224
	ds_read_b128 v[212:215], v172 offset:53248
	ds_read_b128 v[216:219], v172 offset:54272
	ds_read_b128 v[220:223], v172 offset:55296
	ds_read_b128 v[234:237], v172 offset:56320
	global_load_lds_dwordx4 v[182:183], off
	s_add_i32 m0, s33, 0x2000
	s_add_u32 s36, s36, 0x80080
	v_lshl_add_u64 v[182:183], v[188:189], 0, s[28:29]
	s_addc_u32 s37, s37, 0
	s_add_i32 s33, s61, s47
	global_load_lds_dwordx4 v[182:183], off
	v_lshl_add_u64 v[182:183], s[36:37], 0, v[138:139]
	s_mov_b32 m0, s33
	s_nop 0
	global_load_lds_dwordx4 v[182:183], off
	v_lshl_add_u64 v[182:183], s[36:37], 0, v[142:143]
	s_add_i32 m0, s33, 0x2000
	s_nop 0
	global_load_lds_dwordx4 v[182:183], off
	v_lshl_add_u64 v[182:183], v[190:191], 0, s[28:29]
	s_mov_b32 m0, s52
	s_nop 0
	global_load_lds_dwordx4 v[182:183], off
	v_lshl_add_u64 v[182:183], v[196:197], 0, s[28:29]
	s_mov_b32 m0, s53
	s_nop 0
	global_load_lds_dwordx4 v[182:183], off
	s_waitcnt vmcnt(8)
	s_waitcnt lgkmcnt(0)
	s_barrier
	s_setprio 0
	s_waitcnt lgkmcnt(0)
	v_mfma_f32_16x16x32_bf16 v[92:95], v[104:107], v[178:181], v[92:95]
	v_mfma_f32_16x16x32_bf16 v[88:91], v[150:153], v[178:181], v[88:91]
	v_mfma_f32_16x16x32_bf16 v[84:87], v[104:107], v[204:207], v[84:87]
	v_mfma_f32_16x16x32_bf16 v[80:83], v[150:153], v[204:207], v[80:83]
	v_mfma_f32_16x16x32_bf16 v[76:79], v[104:107], v[212:215], v[76:79]
	v_mfma_f32_16x16x32_bf16 v[72:75], v[150:153], v[212:215], v[72:75]
	v_mfma_f32_16x16x32_bf16 v[68:71], v[104:107], v[220:223], v[68:71]
	v_mfma_f32_16x16x32_bf16 v[64:67], v[150:153], v[220:223], v[64:67]
	v_mfma_f32_16x16x32_bf16 v[92:95], v[108:111], v[200:203], v[92:95]
	v_mfma_f32_16x16x32_bf16 v[88:91], v[154:157], v[200:203], v[88:91]
	v_mfma_f32_16x16x32_bf16 v[84:87], v[108:111], v[208:211], v[84:87]
	v_mfma_f32_16x16x32_bf16 v[80:83], v[154:157], v[208:211], v[80:83]
	v_mfma_f32_16x16x32_bf16 v[76:79], v[108:111], v[216:219], v[76:79]
	v_mfma_f32_16x16x32_bf16 v[72:75], v[154:157], v[216:219], v[72:75]
	v_mfma_f32_16x16x32_bf16 v[68:71], v[108:111], v[234:237], v[68:71]
	v_mfma_f32_16x16x32_bf16 v[64:67], v[154:157], v[234:237], v[64:67]
	v_mfma_f32_16x16x32_bf16 v[28:31], v[158:161], v[178:181], v[28:31]
	v_mfma_f32_16x16x32_bf16 v[24:27], v[166:169], v[178:181], v[24:27]
	v_mfma_f32_16x16x32_bf16 v[20:23], v[158:161], v[204:207], v[20:23]
	v_mfma_f32_16x16x32_bf16 v[16:19], v[166:169], v[204:207], v[16:19]
	v_mfma_f32_16x16x32_bf16 v[12:15], v[158:161], v[212:215], v[12:15]
	v_mfma_f32_16x16x32_bf16 v[8:11], v[166:169], v[212:215], v[8:11]
	v_mfma_f32_16x16x32_bf16 v[4:7], v[158:161], v[220:223], v[4:7]
	v_mfma_f32_16x16x32_bf16 v[0:3], v[166:169], v[220:223], v[0:3]
	v_mfma_f32_16x16x32_bf16 v[28:31], v[162:165], v[200:203], v[28:31]
	v_mfma_f32_16x16x32_bf16 v[24:27], v[174:177], v[200:203], v[24:27]
	v_mfma_f32_16x16x32_bf16 v[20:23], v[162:165], v[208:211], v[20:23]
	v_mfma_f32_16x16x32_bf16 v[16:19], v[174:177], v[208:211], v[16:19]
	v_mfma_f32_16x16x32_bf16 v[12:15], v[162:165], v[216:219], v[12:15]
	v_mfma_f32_16x16x32_bf16 v[8:11], v[174:177], v[216:219], v[8:11]
	v_mfma_f32_16x16x32_bf16 v[4:7], v[162:165], v[234:237], v[4:7]
	v_mfma_f32_16x16x32_bf16 v[0:3], v[174:177], v[234:237], v[0:3]
	s_setprio 1
	s_barrier
	s_add_i32 s23, s23, 2
	s_add_u32 s34, s34, 0x100
	s_addc_u32 s35, s35, 0
	s_add_u32 s17, s17, 0x100
	s_addc_u32 s19, s19, 0
	s_cmp_gt_u32 s23, 29
	s_cbranch_scc0 .LBB0_378
	s_and_b64 vcc, exec, s[14:15]
	s_cbranch_vccz .LBB0_381
	s_barrier

; #define PG8_STAGE(bufoff, gbase, voff) do { _Pragma("unroll") for (int _i = 0; _i < 2; ++_i) \
;         __builtin_amdgcn_global_load_lds((const unsigned*)((const char*)(gbase) + (voff)[_i]), (LAS unsigned*)(lds + (bufoff) + ldsw + _i * 8192), 16, 0, 0); } while (0)
; #define PG8_LDA(dst, b, h) do { _Pragma("unroll") for (int m = 0; m < 4; ++m) _Pragma("unroll") for (int k = 0; k < 2; ++k) dst[m][k] = *(const LAS bf16x8*)(lds + PG8_SA(b, h) + aoff + m * 2048 + k * 1024); } while (0)
; #define PG8_LDB(dst, b, h) do { _Pragma("unroll") for (int n = 0; n < 2; ++n) _Pragma("unroll") for (int k = 0; k < 2; ++k) dst[n][k] = *(const LAS bf16x8*)(lds + PG8_SB(b, h) + boff + n * 2048 + k * 1024); } while (0)
; #define PG8_MMA(ai, bj, At, Bt) do { __builtin_amdgcn_s_setprio(1); _Pragma("unroll") for (int m = 0; m < 4; ++m) _Pragma("unroll") for (int n = 0; n < 2; ++n) _Pragma("unroll") for (int k = 0; k < 2; ++k) \
;         acc[ai][bj][m][n] = __builtin_amdgcn_mfma_f32_16x16x32_bf16(Bt[n][k], At[m][k], acc[ai][bj][m][n], 0, 0, 0); __builtin_amdgcn_s_setprio(0); } while (0)
; #define PG8_WAIT_V(n) asm volatile("s_waitcnt vmcnt(" #n ")" ::: "memory")
; #define PG8_WAIT_L(n) asm volatile("s_waitcnt lgkmcnt(" #n ")" ::: "memory")
; #define PG8_BAR __builtin_amdgcn_s_barrier()
; #define PG8_SCHED __builtin_amdgcn_sched_barrier(0)
; template <class Epi, class Sched>
; DI void gemm_phase(LAS unsigned char* lds, const int wv, const int lda, const int ldb, const Sched& S, const Epi& E) {
;     ...
;             const bool last = (t == nt - 2);
;             const char* a1 = cA + (size_t)(t + 1) * kstep;
;             const char* a2 = last ? nA : cA + (size_t)(t + 2) * kstep; const char* b2 = last ? nB : cB + (size_t)(t + 2) * kstep;
;             const char* a3 = a2 + kstep; const char* b3 = b2 + kstep;
;             PG8_LDB(B0, 0, 0); PG8_LDB(B1, 0, 1); PG8_SCHED; PG8_LDA(At, 0, 0); PG8_STAGE(PG8_SA(1, 1), a1 + hstepA, voffA);
;             PG8_WAIT_V(8); PG8_WAIT_L(0); PG8_BAR; PG8_MMA(0, 0, At, B0); PG8_MMA(0, 1, At, B1); PG8_BAR; PG8_SCHED;
;             PG8_LDA(At, 0, 1); PG8_STAGE(PG8_SB(0, 0), b2, voffB); PG8_STAGE(PG8_SB(0, 1), b2 + hstepB, voffB); PG8_STAGE(PG8_SA(0, 0), a2, voffA);
;             PG8_WAIT_V(8); PG8_WAIT_L(0); PG8_BAR; PG8_MMA(1, 0, At, B0); PG8_MMA(1, 1, At, B1); PG8_BAR; PG8_SCHED;
.LBB0_1099:
	s_add_u32 s24, s22, 0x100
	s_addc_u32 s25, s23, 0
	s_add_i32 s50, 0, 0x10000
	s_cmp_eq_u32 s49, 8
	s_cselect_b32 s31, s7, s25
	s_cselect_b32 s30, s6, s24
	s_cselect_b32 s27, s19, s1
	s_cselect_b32 s26, s18, s0
	s_add_i32 s51, 0, 0x14000
	v_add_u32_e32 v108, s50, v204
	v_add_u32_e32 v156, s51, v204
	ds_read_b128 v[64:67], v108
	ds_read_b128 v[68:71], v108 offset:1024
	ds_read_b128 v[104:107], v108 offset:2048
	ds_read_b128 v[108:111], v108 offset:3072
	ds_read_b128 v[144:147], v156
	ds_read_b128 v[148:151], v156 offset:1024
	ds_read_b128 v[152:155], v156 offset:2048
	ds_read_b128 v[156:159], v156 offset:3072
	v_lshl_add_u64 v[182:183], s[22:23], 0, v[174:175]
	s_add_i32 m0, s38, 0xc000
	ds_read_b128 v[160:163], v206
	ds_read_b128 v[164:167], v206 offset:1024
	ds_read_b128 v[178:181], v206 offset:2048
	ds_read_b128 v[188:191], v206 offset:3072
	ds_read_b128 v[196:199], v206 offset:4096
	ds_read_b128 v[200:203], v206 offset:5120
	ds_read_b128 v[208:211], v206 offset:6144
	ds_read_b128 v[212:215], v206 offset:7168
	global_load_lds_dwordx4 v[182:183], off
	v_lshl_add_u64 v[182:183], s[22:23], 0, v[176:177]
	s_add_i32 m0, s38, 0xe000
	s_nop 0
	global_load_lds_dwordx4 v[182:183], off
	s_waitcnt vmcnt(8)
	s_waitcnt lgkmcnt(0)
	s_barrier
	s_setprio 0
	s_waitcnt lgkmcnt(0)
	v_mfma_f32_16x16x32_bf16 v[140:143], v[64:67], v[160:163], v[140:143]
	v_mfma_f32_16x16x32_bf16 v[136:139], v[104:107], v[160:163], v[136:139]
	v_mfma_f32_16x16x32_bf16 v[132:135], v[64:67], v[178:181], v[132:135]
	v_mfma_f32_16x16x32_bf16 v[128:131], v[104:107], v[178:181], v[128:131]
	v_mfma_f32_16x16x32_bf16 v[124:127], v[64:67], v[196:199], v[124:127]
	v_mfma_f32_16x16x32_bf16 v[120:123], v[104:107], v[196:199], v[120:123]
	v_mfma_f32_16x16x32_bf16 v[116:119], v[64:67], v[208:211], v[116:119]
	v_mfma_f32_16x16x32_bf16 v[112:115], v[104:107], v[208:211], v[112:115]
	v_mfma_f32_16x16x32_bf16 v[140:143], v[68:71], v[164:167], v[140:143]
	v_mfma_f32_16x16x32_bf16 v[136:139], v[108:111], v[164:167], v[136:139]
	v_mfma_f32_16x16x32_bf16 v[132:135], v[68:71], v[188:191], v[132:135]
	v_mfma_f32_16x16x32_bf16 v[128:131], v[108:111], v[188:191], v[128:131]
	v_mfma_f32_16x16x32_bf16 v[124:127], v[68:71], v[200:203], v[124:127]
	v_mfma_f32_16x16x32_bf16 v[120:123], v[108:111], v[200:203], v[120:123]
	v_mfma_f32_16x16x32_bf16 v[116:119], v[68:71], v[212:215], v[116:119]
	v_mfma_f32_16x16x32_bf16 v[112:115], v[108:111], v[212:215], v[112:115]
	v_mfma_f32_16x16x32_bf16 v[100:103], v[144:147], v[160:163], v[100:103]
	v_mfma_f32_16x16x32_bf16 v[96:99], v[152:155], v[160:163], v[96:99]
	v_mfma_f32_16x16x32_bf16 v[92:95], v[144:147], v[178:181], v[92:95]
	v_mfma_f32_16x16x32_bf16 v[88:91], v[152:155], v[178:181], v[88:91]
	v_mfma_f32_16x16x32_bf16 v[84:87], v[144:147], v[196:199], v[84:87]
	v_mfma_f32_16x16x32_bf16 v[80:83], v[152:155], v[196:199], v[80:83]
	v_mfma_f32_16x16x32_bf16 v[76:79], v[144:147], v[208:211], v[76:79]
	v_mfma_f32_16x16x32_bf16 v[72:75], v[152:155], v[208:211], v[72:75]
	v_mfma_f32_16x16x32_bf16 v[100:103], v[148:151], v[164:167], v[100:103]
	v_mfma_f32_16x16x32_bf16 v[96:99], v[156:159], v[164:167], v[96:99]
	v_mfma_f32_16x16x32_bf16 v[92:95], v[148:151], v[188:191], v[92:95]
	v_mfma_f32_16x16x32_bf16 v[88:91], v[156:159], v[188:191], v[88:91]
	v_mfma_f32_16x16x32_bf16 v[84:87], v[148:151], v[200:203], v[84:87]
	v_mfma_f32_16x16x32_bf16 v[80:83], v[156:159], v[200:203], v[80:83]
	v_mfma_f32_16x16x32_bf16 v[76:79], v[148:151], v[212:215], v[76:79]
	v_mfma_f32_16x16x32_bf16 v[72:75], v[156:159], v[212:215], v[72:75]
	s_setprio 1
	s_barrier
	s_add_i32 s22, s50, s36
	v_lshl_add_u64 v[182:183], s[26:27], 0, v[184:185]
	s_mov_b32 m0, s22
	ds_read_b128 v[160:163], v206 offset:16384
	ds_read_b128 v[164:167], v206 offset:17408
	ds_read_b128 v[178:181], v206 offset:18432
	ds_read_b128 v[188:191], v206 offset:19456
	ds_read_b128 v[196:199], v206 offset:20480
	ds_read_b128 v[200:203], v206 offset:21504
	ds_read_b128 v[208:211], v206 offset:22528
	ds_read_b128 v[212:215], v206 offset:23552
	global_load_lds_dwordx4 v[182:183], off
	s_add_i32 m0, s22, 0x2000
	s_add_u32 s22, s26, 0x30000
	v_lshl_add_u64 v[216:217], s[26:27], 0, v[168:169]
	s_addc_u32 s23, s27, 0
	s_add_i32 s50, s51, s36
	global_load_lds_dwordx4 v[216:217], off
	v_lshl_add_u64 v[218:219], s[22:23], 0, v[184:185]
	s_mov_b32 m0, s50
	v_lshl_add_u64 v[220:221], s[30:31], 0, v[170:171]
	global_load_lds_dwordx4 v[218:219], off
	v_lshl_add_u64 v[218:219], s[22:23], 0, v[168:169]
	s_add_i32 m0, s50, 0x2000
	s_nop 0
	global_load_lds_dwordx4 v[218:219], off
	v_lshl_add_u64 v[218:219], s[30:31], 0, v[172:173]
	s_mov_b32 m0, s38
	s_nop 0
	global_load_lds_dwordx4 v[218:219], off
	s_mov_b32 m0, s39
	s_nop 0
	global_load_lds_dwordx4 v[220:221], off
	s_waitcnt vmcnt(8)
	s_waitcnt lgkmcnt(0)
	s_barrier
; #define PG8_STAGE(bufoff, gbase, voff) do { _Pragma("unroll") for (int _i = 0; _i < 2; ++_i) \
;         __builtin_amdgcn_global_load_lds((const unsigned*)((const char*)(gbase) + (voff)[_i]), (LAS unsigned*)(lds + (bufoff) + ldsw + _i * 8192), 16, 0, 0); } while (0)
; #define PG8_LDA(dst, b, h) do { _Pragma("unroll") for (int m = 0; m < 4; ++m) _Pragma("unroll") for (int k = 0; k < 2; ++k) dst[m][k] = *(const LAS bf16x8*)(lds + PG8_SA(b, h) + aoff + m * 2048 + k * 1024); } while (0)
; #define PG8_LDB(dst, b, h) do { _Pragma("unroll") for (int n = 0; n < 2; ++n) _Pragma("unroll") for (int k = 0; k < 2; ++k) dst[n][k] = *(const LAS bf16x8*)(lds + PG8_SB(b, h) + boff + n * 2048 + k * 1024); } while (0)
; #define PG8_MMA(ai, bj, At, Bt) do { __builtin_amdgcn_s_setprio(1); _Pragma("unroll") for (int m = 0; m < 4; ++m) _Pragma("unroll") for (int n = 0; n < 2; ++n) _Pragma("unroll") for (int k = 0; k < 2; ++k) \
;         acc[ai][bj][m][n] = __builtin_amdgcn_mfma_f32_16x16x32_bf16(Bt[n][k], At[m][k], acc[ai][bj][m][n], 0, 0, 0); __builtin_amdgcn_s_setprio(0); } while (0)
; #define PG8_WAIT_V(n) asm volatile("s_waitcnt vmcnt(" #n ")" ::: "memory")
; #define PG8_WAIT_L(n) asm volatile("s_waitcnt lgkmcnt(" #n ")" ::: "memory")
; #define PG8_BAR __builtin_amdgcn_s_barrier()
; #define PG8_SCHED __builtin_amdgcn_sched_barrier(0)
; template <class Epi, class Sched>
; DI void gemm_phase(LAS unsigned char* lds, const int wv, const int lda, const int ldb, const Sched& S, const Epi& E) {
;     ...
;             PG8_WAIT_V(8); PG8_WAIT_L(0); PG8_BAR; PG8_MMA(1, 0, At, B0); PG8_MMA(1, 1, At, B1); PG8_BAR; PG8_SCHED;
;             PG8_LDB(B0, 1, 0); PG8_LDB(B1, 1, 1); PG8_SCHED; PG8_LDA(At, 1, 0); PG8_STAGE(PG8_SA(0, 1), a2 + hstepA, voffA);
;             PG8_WAIT_V(8); PG8_WAIT_L(0); PG8_BAR; PG8_MMA(0, 0, At, B0); PG8_MMA(0, 1, At, B1); PG8_BAR; PG8_SCHED;
	s_setprio 0
	s_waitcnt lgkmcnt(0)
	v_mfma_f32_16x16x32_bf16 v[60:63], v[64:67], v[160:163], v[60:63]
	v_mfma_f32_16x16x32_bf16 v[56:59], v[104:107], v[160:163], v[56:59]
	v_mfma_f32_16x16x32_bf16 v[52:55], v[64:67], v[178:181], v[52:55]
	v_mfma_f32_16x16x32_bf16 v[48:51], v[104:107], v[178:181], v[48:51]
	v_mfma_f32_16x16x32_bf16 v[44:47], v[64:67], v[196:199], v[44:47]
	v_mfma_f32_16x16x32_bf16 v[40:43], v[104:107], v[196:199], v[40:43]
	v_mfma_f32_16x16x32_bf16 v[36:39], v[64:67], v[208:211], v[36:39]
	v_mfma_f32_16x16x32_bf16 v[32:35], v[104:107], v[208:211], v[32:35]
	v_mfma_f32_16x16x32_bf16 v[60:63], v[68:71], v[164:167], v[60:63]
	v_mfma_f32_16x16x32_bf16 v[56:59], v[108:111], v[164:167], v[56:59]
	v_mfma_f32_16x16x32_bf16 v[52:55], v[68:71], v[188:191], v[52:55]
	v_mfma_f32_16x16x32_bf16 v[48:51], v[108:111], v[188:191], v[48:51]
	v_mfma_f32_16x16x32_bf16 v[44:47], v[68:71], v[200:203], v[44:47]
	v_mfma_f32_16x16x32_bf16 v[40:43], v[108:111], v[200:203], v[40:43]
	v_mfma_f32_16x16x32_bf16 v[36:39], v[68:71], v[212:215], v[36:39]
	v_mfma_f32_16x16x32_bf16 v[32:35], v[108:111], v[212:215], v[32:35]
	v_mfma_f32_16x16x32_bf16 v[28:31], v[144:147], v[160:163], v[28:31]
	v_mfma_f32_16x16x32_bf16 v[24:27], v[152:155], v[160:163], v[24:27]
	v_mfma_f32_16x16x32_bf16 v[20:23], v[144:147], v[178:181], v[20:23]
	v_mfma_f32_16x16x32_bf16 v[16:19], v[152:155], v[178:181], v[16:19]
	v_mfma_f32_16x16x32_bf16 v[12:15], v[144:147], v[196:199], v[12:15]
	v_mfma_f32_16x16x32_bf16 v[8:11], v[152:155], v[196:199], v[8:11]
	v_mfma_f32_16x16x32_bf16 v[4:7], v[144:147], v[208:211], v[4:7]
	v_mfma_f32_16x16x32_bf16 v[0:3], v[152:155], v[208:211], v[0:3]
	v_mfma_f32_16x16x32_bf16 v[28:31], v[148:151], v[164:167], v[28:31]
	v_mfma_f32_16x16x32_bf16 v[24:27], v[156:159], v[164:167], v[24:27]
	v_mfma_f32_16x16x32_bf16 v[20:23], v[148:151], v[188:191], v[20:23]
	v_mfma_f32_16x16x32_bf16 v[16:19], v[156:159], v[188:191], v[16:19]
	v_mfma_f32_16x16x32_bf16 v[12:15], v[148:151], v[200:203], v[12:15]
	v_mfma_f32_16x16x32_bf16 v[8:11], v[156:159], v[200:203], v[8:11]
	v_mfma_f32_16x16x32_bf16 v[4:7], v[148:151], v[212:215], v[4:7]
	v_mfma_f32_16x16x32_bf16 v[0:3], v[156:159], v[212:215], v[0:3]
	s_setprio 1
	s_barrier
	s_add_i32 s50, 0, 0x18000
	s_add_i32 s51, 0, 0x1c000
	v_add_u32_e32 v108, s50, v204
	v_add_u32_e32 v156, s51, v204
	ds_read_b128 v[64:67], v108
	ds_read_b128 v[68:71], v108 offset:1024
	ds_read_b128 v[104:107], v108 offset:2048
	ds_read_b128 v[108:111], v108 offset:3072
	ds_read_b128 v[144:147], v156
	ds_read_b128 v[148:151], v156 offset:1024
	ds_read_b128 v[152:155], v156 offset:2048
	ds_read_b128 v[156:159], v156 offset:3072
	s_add_u32 s22, s30, 0x30000
	s_addc_u32 s23, s31, 0
	s_mov_b32 m0, s40
	v_lshl_add_u64 v[222:223], s[22:23], 0, v[172:173]
	ds_read_b128 v[160:163], v206 offset:32768
	ds_read_b128 v[164:167], v206 offset:33792
	ds_read_b128 v[178:181], v206 offset:34816
	ds_read_b128 v[188:191], v206 offset:35840
	ds_read_b128 v[196:199], v206 offset:36864
	ds_read_b128 v[200:203], v206 offset:37888
	ds_read_b128 v[208:211], v206 offset:38912
	ds_read_b128 v[212:215], v206 offset:39936
	global_load_lds_dwordx4 v[222:223], off
	v_lshl_add_u64 v[222:223], s[22:23], 0, v[170:171]
	s_mov_b32 m0, s41
	s_nop 0
	global_load_lds_dwordx4 v[222:223], off
	s_waitcnt vmcnt(8)
	s_waitcnt lgkmcnt(0)
	s_barrier
	s_setprio 0
	s_waitcnt lgkmcnt(0)
	v_mfma_f32_16x16x32_bf16 v[140:143], v[64:67], v[160:163], v[140:143]
	v_mfma_f32_16x16x32_bf16 v[136:139], v[104:107], v[160:163], v[136:139]
	v_mfma_f32_16x16x32_bf16 v[132:135], v[64:67], v[178:181], v[132:135]
	v_mfma_f32_16x16x32_bf16 v[128:131], v[104:107], v[178:181], v[128:131]
	v_mfma_f32_16x16x32_bf16 v[124:127], v[64:67], v[196:199], v[124:127]
	v_mfma_f32_16x16x32_bf16 v[120:123], v[104:107], v[196:199], v[120:123]
	v_mfma_f32_16x16x32_bf16 v[116:119], v[64:67], v[208:211], v[116:119]
	v_mfma_f32_16x16x32_bf16 v[112:115], v[104:107], v[208:211], v[112:115]
	v_mfma_f32_16x16x32_bf16 v[140:143], v[68:71], v[164:167], v[140:143]
	v_mfma_f32_16x16x32_bf16 v[136:139], v[108:111], v[164:167], v[136:139]
	v_mfma_f32_16x16x32_bf16 v[132:135], v[68:71], v[188:191], v[132:135]
	v_mfma_f32_16x16x32_bf16 v[128:131], v[108:111], v[188:191], v[128:131]
	v_mfma_f32_16x16x32_bf16 v[124:127], v[68:71], v[200:203], v[124:127]
	v_mfma_f32_16x16x32_bf16 v[120:123], v[108:111], v[200:203], v[120:123]
	v_mfma_f32_16x16x32_bf16 v[116:119], v[68:71], v[212:215], v[116:119]
	v_mfma_f32_16x16x32_bf16 v[112:115], v[108:111], v[212:215], v[112:115]
	v_mfma_f32_16x16x32_bf16 v[100:103], v[144:147], v[160:163], v[100:103]
	v_mfma_f32_16x16x32_bf16 v[96:99], v[152:155], v[160:163], v[96:99]
	v_mfma_f32_16x16x32_bf16 v[92:95], v[144:147], v[178:181], v[92:95]
	v_mfma_f32_16x16x32_bf16 v[88:91], v[152:155], v[178:181], v[88:91]
	v_mfma_f32_16x16x32_bf16 v[84:87], v[144:147], v[196:199], v[84:87]
	v_mfma_f32_16x16x32_bf16 v[80:83], v[152:155], v[196:199], v[80:83]
	v_mfma_f32_16x16x32_bf16 v[76:79], v[144:147], v[208:211], v[76:79]
	v_mfma_f32_16x16x32_bf16 v[72:75], v[152:155], v[208:211], v[72:75]
	v_mfma_f32_16x16x32_bf16 v[100:103], v[148:151], v[164:167], v[100:103]
	v_mfma_f32_16x16x32_bf16 v[96:99], v[156:159], v[164:167], v[96:99]
	v_mfma_f32_16x16x32_bf16 v[92:95], v[148:151], v[188:191], v[92:95]
	v_mfma_f32_16x16x32_bf16 v[88:91], v[156:159], v[188:191], v[88:91]
	v_mfma_f32_16x16x32_bf16 v[84:87], v[148:151], v[200:203], v[84:87]
	v_mfma_f32_16x16x32_bf16 v[80:83], v[156:159], v[200:203], v[80:83]
	v_mfma_f32_16x16x32_bf16 v[76:79], v[148:151], v[212:215], v[76:79]
	v_mfma_f32_16x16x32_bf16 v[72:75], v[156:159], v[212:215], v[72:75]
	s_setprio 1
	s_barrier
; #define PG8_STAGE(bufoff, gbase, voff) do { _Pragma("unroll") for (int _i = 0; _i < 2; ++_i) \
;         __builtin_amdgcn_global_load_lds((const unsigned*)((const char*)(gbase) + (voff)[_i]), (LAS unsigned*)(lds + (bufoff) + ldsw + _i * 8192), 16, 0, 0); } while (0)
; #define PG8_LDA(dst, b, h) do { _Pragma("unroll") for (int m = 0; m < 4; ++m) _Pragma("unroll") for (int k = 0; k < 2; ++k) dst[m][k] = *(const LAS bf16x8*)(lds + PG8_SA(b, h) + aoff + m * 2048 + k * 1024); } while (0)
; #define PG8_MMA(ai, bj, At, Bt) do { __builtin_amdgcn_s_setprio(1); _Pragma("unroll") for (int m = 0; m < 4; ++m) _Pragma("unroll") for (int n = 0; n < 2; ++n) _Pragma("unroll") for (int k = 0; k < 2; ++k) \
;         acc[ai][bj][m][n] = __builtin_amdgcn_mfma_f32_16x16x32_bf16(Bt[n][k], At[m][k], acc[ai][bj][m][n], 0, 0, 0); __builtin_amdgcn_s_setprio(0); } while (0)
; #define PG8_WAIT_V(n) asm volatile("s_waitcnt vmcnt(" #n ")" ::: "memory")
; #define PG8_WAIT_L(n) asm volatile("s_waitcnt lgkmcnt(" #n ")" ::: "memory")
; #define PG8_BAR __builtin_amdgcn_s_barrier()
; #define PG8_SCHED __builtin_amdgcn_sched_barrier(0)
; template <class Epi, class Sched>
; DI void gemm_phase(LAS unsigned char* lds, const int wv, const int lda, const int ldb, const Sched& S, const Epi& E) {
;     ...
;             PG8_LDA(At, 1, 1); PG8_STAGE(PG8_SB(1, 0), b3, voffB); PG8_STAGE(PG8_SB(1, 1), b3 + hstepB, voffB); PG8_STAGE(PG8_SA(1, 0), a3, voffA);
;             PG8_WAIT_V(8); PG8_WAIT_L(0); PG8_BAR; PG8_MMA(1, 0, At, B0); PG8_MMA(1, 1, At, B1); PG8_BAR; PG8_SCHED;
;         }
;         if (wr == 0) PG8_BAR;
	s_add_i32 s22, s50, s36
	v_lshl_add_u64 v[182:183], v[182:183], 0, s[28:29]
	s_mov_b32 m0, s22
	ds_read_b128 v[160:163], v206 offset:49152
	ds_read_b128 v[164:167], v206 offset:50176
	ds_read_b128 v[178:181], v206 offset:51200
	ds_read_b128 v[188:191], v206 offset:52224
	ds_read_b128 v[196:199], v206 offset:53248
	ds_read_b128 v[200:203], v206 offset:54272
	ds_read_b128 v[208:211], v206 offset:55296
	ds_read_b128 v[212:215], v206 offset:56320
	global_load_lds_dwordx4 v[182:183], off
	s_add_i32 m0, s22, 0x2000
	s_add_u32 s22, s26, 0x30080
	v_lshl_add_u64 v[182:183], v[216:217], 0, s[28:29]
	s_addc_u32 s23, s27, 0
	s_add_i32 s26, s51, s36
	global_load_lds_dwordx4 v[182:183], off
	v_lshl_add_u64 v[182:183], s[22:23], 0, v[184:185]
	s_mov_b32 m0, s26
	s_nop 0
	global_load_lds_dwordx4 v[182:183], off
	v_lshl_add_u64 v[182:183], s[22:23], 0, v[168:169]
	s_add_i32 m0, s26, 0x2000
	s_nop 0
	global_load_lds_dwordx4 v[182:183], off
	v_lshl_add_u64 v[182:183], v[218:219], 0, s[28:29]
	s_mov_b32 m0, s20
	s_nop 0
	global_load_lds_dwordx4 v[182:183], off
	v_lshl_add_u64 v[182:183], v[220:221], 0, s[28:29]
	s_mov_b32 m0, s42
	s_nop 0
	global_load_lds_dwordx4 v[182:183], off
	s_waitcnt vmcnt(8)
	s_waitcnt lgkmcnt(0)
	s_barrier
	s_setprio 0
	s_waitcnt lgkmcnt(0)
	v_mfma_f32_16x16x32_bf16 v[60:63], v[64:67], v[160:163], v[60:63]
	v_mfma_f32_16x16x32_bf16 v[56:59], v[104:107], v[160:163], v[56:59]
	v_mfma_f32_16x16x32_bf16 v[52:55], v[64:67], v[178:181], v[52:55]
	v_mfma_f32_16x16x32_bf16 v[48:51], v[104:107], v[178:181], v[48:51]
	v_mfma_f32_16x16x32_bf16 v[44:47], v[64:67], v[196:199], v[44:47]
	v_mfma_f32_16x16x32_bf16 v[40:43], v[104:107], v[196:199], v[40:43]
	v_mfma_f32_16x16x32_bf16 v[36:39], v[64:67], v[208:211], v[36:39]
	v_mfma_f32_16x16x32_bf16 v[32:35], v[104:107], v[208:211], v[32:35]
	v_mfma_f32_16x16x32_bf16 v[60:63], v[68:71], v[164:167], v[60:63]
	v_mfma_f32_16x16x32_bf16 v[56:59], v[108:111], v[164:167], v[56:59]
	v_mfma_f32_16x16x32_bf16 v[52:55], v[68:71], v[188:191], v[52:55]
	v_mfma_f32_16x16x32_bf16 v[48:51], v[108:111], v[188:191], v[48:51]
	v_mfma_f32_16x16x32_bf16 v[44:47], v[68:71], v[200:203], v[44:47]
	v_mfma_f32_16x16x32_bf16 v[40:43], v[108:111], v[200:203], v[40:43]
	v_mfma_f32_16x16x32_bf16 v[36:39], v[68:71], v[212:215], v[36:39]
	v_mfma_f32_16x16x32_bf16 v[32:35], v[108:111], v[212:215], v[32:35]
	v_mfma_f32_16x16x32_bf16 v[28:31], v[144:147], v[160:163], v[28:31]
	v_mfma_f32_16x16x32_bf16 v[24:27], v[152:155], v[160:163], v[24:27]
	v_mfma_f32_16x16x32_bf16 v[20:23], v[144:147], v[178:181], v[20:23]
	v_mfma_f32_16x16x32_bf16 v[16:19], v[152:155], v[178:181], v[16:19]
	v_mfma_f32_16x16x32_bf16 v[12:15], v[144:147], v[196:199], v[12:15]
	v_mfma_f32_16x16x32_bf16 v[8:11], v[152:155], v[196:199], v[8:11]
	v_mfma_f32_16x16x32_bf16 v[4:7], v[144:147], v[208:211], v[4:7]
	v_mfma_f32_16x16x32_bf16 v[0:3], v[152:155], v[208:211], v[0:3]
	v_mfma_f32_16x16x32_bf16 v[28:31], v[148:151], v[164:167], v[28:31]
	v_mfma_f32_16x16x32_bf16 v[24:27], v[156:159], v[164:167], v[24:27]
	v_mfma_f32_16x16x32_bf16 v[20:23], v[148:151], v[188:191], v[20:23]
	v_mfma_f32_16x16x32_bf16 v[16:19], v[156:159], v[188:191], v[16:19]
	v_mfma_f32_16x16x32_bf16 v[12:15], v[148:151], v[200:203], v[12:15]
	v_mfma_f32_16x16x32_bf16 v[8:11], v[156:159], v[200:203], v[8:11]
	v_mfma_f32_16x16x32_bf16 v[4:7], v[148:151], v[212:215], v[4:7]
	v_mfma_f32_16x16x32_bf16 v[0:3], v[156:159], v[212:215], v[0:3]
	s_setprio 1
	s_barrier
	s_add_i32 s49, s49, 2
	s_add_u32 s0, s0, 0x100
	s_addc_u32 s1, s1, 0
	s_cmp_gt_u32 s49, 9
	s_mov_b64 s[22:23], s[24:25]
	s_cbranch_scc0 .LBB0_1099
	s_and_b64 vcc, exec, s[14:15]
	s_cbranch_vccz .LBB0_1102
	s_barrier

; #define PG8_STAGE(bufoff, gbase, voff) do { _Pragma("unroll") for (int _i = 0; _i < 2; ++_i) \
;         __builtin_amdgcn_global_load_lds((const unsigned*)((const char*)(gbase) + (voff)[_i]), (LAS unsigned*)(lds + (bufoff) + ldsw + _i * 8192), 16, 0, 0); } while (0)
; #define PG8_LDA(dst, b, h) do { _Pragma("unroll") for (int m = 0; m < 4; ++m) _Pragma("unroll") for (int k = 0; k < 2; ++k) dst[m][k] = *(const LAS bf16x8*)(lds + PG8_SA(b, h) + aoff + m * 2048 + k * 1024); } while (0)
; #define PG8_LDB(dst, b, h) do { _Pragma("unroll") for (int n = 0; n < 2; ++n) _Pragma("unroll") for (int k = 0; k < 2; ++k) dst[n][k] = *(const LAS bf16x8*)(lds + PG8_SB(b, h) + boff + n * 2048 + k * 1024); } while (0)
; #define PG8_MMA(ai, bj, At, Bt) do { __builtin_amdgcn_s_setprio(1); _Pragma("unroll") for (int m = 0; m < 4; ++m) _Pragma("unroll") for (int n = 0; n < 2; ++n) _Pragma("unroll") for (int k = 0; k < 2; ++k) \
;         acc[ai][bj][m][n] = __builtin_amdgcn_mfma_f32_16x16x32_bf16(Bt[n][k], At[m][k], acc[ai][bj][m][n], 0, 0, 0); __builtin_amdgcn_s_setprio(0); } while (0)
; #define PG8_WAIT_V(n) asm volatile("s_waitcnt vmcnt(" #n ")" ::: "memory")
; #define PG8_WAIT_L(n) asm volatile("s_waitcnt lgkmcnt(" #n ")" ::: "memory")
; #define PG8_BAR __builtin_amdgcn_s_barrier()
; #define PG8_SCHED __builtin_amdgcn_sched_barrier(0)
; template <class Epi, class Sched>
; DI void gemm_phase(LAS unsigned char* lds, const int wv, const int lda, const int ldb, const Sched& S, const Epi& E) {
;     ...
;             const bool last = (t == nt - 2);
;             const char* a1 = cA + (size_t)(t + 1) * kstep;
;             const char* a2 = last ? nA : cA + (size_t)(t + 2) * kstep; const char* b2 = last ? nB : cB + (size_t)(t + 2) * kstep;
;             const char* a3 = a2 + kstep; const char* b3 = b2 + kstep;
;             PG8_LDB(B0, 0, 0); PG8_LDB(B1, 0, 1); PG8_SCHED; PG8_LDA(At, 0, 0); PG8_STAGE(PG8_SA(1, 1), a1 + hstepA, voffA);
;             PG8_WAIT_V(8); PG8_WAIT_L(0); PG8_BAR; PG8_MMA(0, 0, At, B0); PG8_MMA(0, 1, At, B1); PG8_BAR; PG8_SCHED;
;             PG8_LDA(At, 0, 1); PG8_STAGE(PG8_SB(0, 0), b2, voffB); PG8_STAGE(PG8_SB(0, 1), b2 + hstepB, voffB); PG8_STAGE(PG8_SA(0, 0), a2, voffA);
;             PG8_WAIT_V(8); PG8_WAIT_L(0); PG8_BAR; PG8_MMA(1, 0, At, B0); PG8_MMA(1, 1, At, B1); PG8_BAR; PG8_SCHED;
.LBB0_1185:
	s_add_i32 s31, s19, 2
	s_add_u32 s34, s6, 0xfff80080
	s_addc_u32 s35, s7, -1
	s_add_i32 s40, 0, 0x10000
	s_cmp_eq_u32 s0, s19
	s_cselect_b32 s37, s23, s35
	s_cselect_b32 s36, s22, s34
	s_cselect_b32 s35, s25, s15
	s_cselect_b32 s34, s24, s1
	s_add_i32 s19, 0, 0x14000
	v_add_u32_e32 v140, s40, v233
	v_add_u32_e32 v156, s19, v233
	ds_read_b128 v[128:131], v140
	ds_read_b128 v[132:135], v140 offset:1024
	ds_read_b128 v[136:139], v140 offset:2048
	ds_read_b128 v[140:143], v140 offset:3072
	ds_read_b128 v[144:147], v156
	ds_read_b128 v[148:151], v156 offset:1024
	ds_read_b128 v[152:155], v156 offset:2048
	ds_read_b128 v[156:159], v156 offset:3072
	v_lshl_add_u64 v[210:211], s[6:7], 0, v[206:207]
	s_add_i32 m0, s45, 0xc000
	ds_read_b128 v[160:163], v235
	ds_read_b128 v[164:167], v235 offset:1024
	ds_read_b128 v[168:171], v235 offset:2048
	ds_read_b128 v[172:175], v235 offset:3072
	ds_read_b128 v[176:179], v235 offset:4096
	ds_read_b128 v[180:183], v235 offset:5120
	ds_read_b128 v[188:191], v235 offset:6144
	ds_read_b128 v[196:199], v235 offset:7168
	global_load_lds_dwordx4 v[210:211], off
	v_lshl_add_u64 v[210:211], s[6:7], 0, v[208:209]
	s_add_i32 m0, s45, 0xe000
	s_nop 0
	global_load_lds_dwordx4 v[210:211], off
	s_waitcnt vmcnt(8)
	s_waitcnt lgkmcnt(0)
	s_barrier
	s_setprio 0
	s_waitcnt lgkmcnt(0)
	v_mfma_f32_16x16x32_bf16 v[124:127], v[128:131], v[160:163], v[124:127]
	v_mfma_f32_16x16x32_bf16 v[120:123], v[136:139], v[160:163], v[120:123]
	v_mfma_f32_16x16x32_bf16 v[116:119], v[128:131], v[168:171], v[116:119]
	v_mfma_f32_16x16x32_bf16 v[112:115], v[136:139], v[168:171], v[112:115]
	v_mfma_f32_16x16x32_bf16 v[108:111], v[128:131], v[176:179], v[108:111]
	v_mfma_f32_16x16x32_bf16 v[104:107], v[136:139], v[176:179], v[104:107]
	v_mfma_f32_16x16x32_bf16 v[100:103], v[128:131], v[188:191], v[100:103]
	v_mfma_f32_16x16x32_bf16 v[96:99], v[136:139], v[188:191], v[96:99]
	v_mfma_f32_16x16x32_bf16 v[124:127], v[132:135], v[164:167], v[124:127]
	v_mfma_f32_16x16x32_bf16 v[120:123], v[140:143], v[164:167], v[120:123]
	v_mfma_f32_16x16x32_bf16 v[116:119], v[132:135], v[172:175], v[116:119]
	v_mfma_f32_16x16x32_bf16 v[112:115], v[140:143], v[172:175], v[112:115]
	v_mfma_f32_16x16x32_bf16 v[108:111], v[132:135], v[180:183], v[108:111]
	v_mfma_f32_16x16x32_bf16 v[104:107], v[140:143], v[180:183], v[104:107]
	v_mfma_f32_16x16x32_bf16 v[100:103], v[132:135], v[196:199], v[100:103]
	v_mfma_f32_16x16x32_bf16 v[96:99], v[140:143], v[196:199], v[96:99]
	v_mfma_f32_16x16x32_bf16 v[92:95], v[144:147], v[160:163], v[92:95]
	v_mfma_f32_16x16x32_bf16 v[88:91], v[152:155], v[160:163], v[88:91]
	v_mfma_f32_16x16x32_bf16 v[84:87], v[144:147], v[168:171], v[84:87]
	v_mfma_f32_16x16x32_bf16 v[80:83], v[152:155], v[168:171], v[80:83]
	v_mfma_f32_16x16x32_bf16 v[76:79], v[144:147], v[176:179], v[76:79]
	v_mfma_f32_16x16x32_bf16 v[72:75], v[152:155], v[176:179], v[72:75]
	v_mfma_f32_16x16x32_bf16 v[68:71], v[144:147], v[188:191], v[68:71]
	v_mfma_f32_16x16x32_bf16 v[64:67], v[152:155], v[188:191], v[64:67]
	v_mfma_f32_16x16x32_bf16 v[92:95], v[148:151], v[164:167], v[92:95]
	v_mfma_f32_16x16x32_bf16 v[88:91], v[156:159], v[164:167], v[88:91]
	v_mfma_f32_16x16x32_bf16 v[84:87], v[148:151], v[172:175], v[84:87]
	v_mfma_f32_16x16x32_bf16 v[80:83], v[156:159], v[172:175], v[80:83]
	v_mfma_f32_16x16x32_bf16 v[76:79], v[148:151], v[180:183], v[76:79]
	v_mfma_f32_16x16x32_bf16 v[72:75], v[156:159], v[180:183], v[72:75]
	v_mfma_f32_16x16x32_bf16 v[68:71], v[148:151], v[196:199], v[68:71]
	v_mfma_f32_16x16x32_bf16 v[64:67], v[156:159], v[196:199], v[64:67]
	s_setprio 1
	s_barrier
	s_add_i32 s40, s40, s44
	v_lshl_add_u64 v[210:211], s[34:35], 0, v[184:185]
	s_mov_b32 m0, s40
	ds_read_b128 v[160:163], v235 offset:16384
	ds_read_b128 v[164:167], v235 offset:17408
	ds_read_b128 v[168:171], v235 offset:18432
	ds_read_b128 v[172:175], v235 offset:19456
	ds_read_b128 v[176:179], v235 offset:20480
	ds_read_b128 v[180:183], v235 offset:21504
	ds_read_b128 v[188:191], v235 offset:22528
	ds_read_b128 v[196:199], v235 offset:23552
	global_load_lds_dwordx4 v[210:211], off
	s_add_i32 m0, s40, 0x2000
	s_add_u32 s40, s34, 0x80000
	v_lshl_add_u64 v[212:213], s[34:35], 0, v[204:205]
	s_addc_u32 s41, s35, 0
	s_add_i32 s19, s19, s44
	global_load_lds_dwordx4 v[212:213], off
	v_lshl_add_u64 v[214:215], s[40:41], 0, v[184:185]
	s_mov_b32 m0, s19
	v_lshl_add_u64 v[216:217], s[36:37], 0, v[202:203]
	global_load_lds_dwordx4 v[214:215], off
	v_lshl_add_u64 v[214:215], s[40:41], 0, v[204:205]
	s_add_i32 m0, s19, 0x2000
	s_nop 0
	global_load_lds_dwordx4 v[214:215], off
	v_lshl_add_u64 v[214:215], s[36:37], 0, v[200:201]
	s_mov_b32 m0, s45
	s_nop 0
	global_load_lds_dwordx4 v[214:215], off
	s_mov_b32 m0, s46
	s_nop 0
	global_load_lds_dwordx4 v[216:217], off
	s_waitcnt vmcnt(8)
	s_waitcnt lgkmcnt(0)
	s_barrier
; #define PG8_STAGE(bufoff, gbase, voff) do { _Pragma("unroll") for (int _i = 0; _i < 2; ++_i) \
;         __builtin_amdgcn_global_load_lds((const unsigned*)((const char*)(gbase) + (voff)[_i]), (LAS unsigned*)(lds + (bufoff) + ldsw + _i * 8192), 16, 0, 0); } while (0)
; #define PG8_LDA(dst, b, h) do { _Pragma("unroll") for (int m = 0; m < 4; ++m) _Pragma("unroll") for (int k = 0; k < 2; ++k) dst[m][k] = *(const LAS bf16x8*)(lds + PG8_SA(b, h) + aoff + m * 2048 + k * 1024); } while (0)
; #define PG8_LDB(dst, b, h) do { _Pragma("unroll") for (int n = 0; n < 2; ++n) _Pragma("unroll") for (int k = 0; k < 2; ++k) dst[n][k] = *(const LAS bf16x8*)(lds + PG8_SB(b, h) + boff + n * 2048 + k * 1024); } while (0)
; #define PG8_MMA(ai, bj, At, Bt) do { __builtin_amdgcn_s_setprio(1); _Pragma("unroll") for (int m = 0; m < 4; ++m) _Pragma("unroll") for (int n = 0; n < 2; ++n) _Pragma("unroll") for (int k = 0; k < 2; ++k) \
;         acc[ai][bj][m][n] = __builtin_amdgcn_mfma_f32_16x16x32_bf16(Bt[n][k], At[m][k], acc[ai][bj][m][n], 0, 0, 0); __builtin_amdgcn_s_setprio(0); } while (0)
; #define PG8_WAIT_V(n) asm volatile("s_waitcnt vmcnt(" #n ")" ::: "memory")
; #define PG8_WAIT_L(n) asm volatile("s_waitcnt lgkmcnt(" #n ")" ::: "memory")
; #define PG8_BAR __builtin_amdgcn_s_barrier()
; #define PG8_SCHED __builtin_amdgcn_sched_barrier(0)
; template <class Epi, class Sched>
; DI void gemm_phase(LAS unsigned char* lds, const int wv, const int lda, const int ldb, const Sched& S, const Epi& E) {
;     ...
;             PG8_WAIT_V(8); PG8_WAIT_L(0); PG8_BAR; PG8_MMA(1, 0, At, B0); PG8_MMA(1, 1, At, B1); PG8_BAR; PG8_SCHED;
;             PG8_LDB(B0, 1, 0); PG8_LDB(B1, 1, 1); PG8_SCHED; PG8_LDA(At, 1, 0); PG8_STAGE(PG8_SA(0, 1), a2 + hstepA, voffA);
;             PG8_WAIT_V(8); PG8_WAIT_L(0); PG8_BAR; PG8_MMA(0, 0, At, B0); PG8_MMA(0, 1, At, B1); PG8_BAR; PG8_SCHED;
	s_setprio 0
	s_waitcnt lgkmcnt(0)
	v_mfma_f32_16x16x32_bf16 v[60:63], v[128:131], v[160:163], v[60:63]
	v_mfma_f32_16x16x32_bf16 v[56:59], v[136:139], v[160:163], v[56:59]
	v_mfma_f32_16x16x32_bf16 v[52:55], v[128:131], v[168:171], v[52:55]
	v_mfma_f32_16x16x32_bf16 v[48:51], v[136:139], v[168:171], v[48:51]
	v_mfma_f32_16x16x32_bf16 v[44:47], v[128:131], v[176:179], v[44:47]
	v_mfma_f32_16x16x32_bf16 v[40:43], v[136:139], v[176:179], v[40:43]
	v_mfma_f32_16x16x32_bf16 v[36:39], v[128:131], v[188:191], v[36:39]
	v_mfma_f32_16x16x32_bf16 v[32:35], v[136:139], v[188:191], v[32:35]
	v_mfma_f32_16x16x32_bf16 v[60:63], v[132:135], v[164:167], v[60:63]
	v_mfma_f32_16x16x32_bf16 v[56:59], v[140:143], v[164:167], v[56:59]
	v_mfma_f32_16x16x32_bf16 v[52:55], v[132:135], v[172:175], v[52:55]
	v_mfma_f32_16x16x32_bf16 v[48:51], v[140:143], v[172:175], v[48:51]
	v_mfma_f32_16x16x32_bf16 v[44:47], v[132:135], v[180:183], v[44:47]
	v_mfma_f32_16x16x32_bf16 v[40:43], v[140:143], v[180:183], v[40:43]
	v_mfma_f32_16x16x32_bf16 v[36:39], v[132:135], v[196:199], v[36:39]
	v_mfma_f32_16x16x32_bf16 v[32:35], v[140:143], v[196:199], v[32:35]
	v_mfma_f32_16x16x32_bf16 v[28:31], v[144:147], v[160:163], v[28:31]
	v_mfma_f32_16x16x32_bf16 v[24:27], v[152:155], v[160:163], v[24:27]
	v_mfma_f32_16x16x32_bf16 v[20:23], v[144:147], v[168:171], v[20:23]
	v_mfma_f32_16x16x32_bf16 v[16:19], v[152:155], v[168:171], v[16:19]
	v_mfma_f32_16x16x32_bf16 v[12:15], v[144:147], v[176:179], v[12:15]
	v_mfma_f32_16x16x32_bf16 v[8:11], v[152:155], v[176:179], v[8:11]
	v_mfma_f32_16x16x32_bf16 v[4:7], v[144:147], v[188:191], v[4:7]
	v_mfma_f32_16x16x32_bf16 v[0:3], v[152:155], v[188:191], v[0:3]
	v_mfma_f32_16x16x32_bf16 v[28:31], v[148:151], v[164:167], v[28:31]
	v_mfma_f32_16x16x32_bf16 v[24:27], v[156:159], v[164:167], v[24:27]
	v_mfma_f32_16x16x32_bf16 v[20:23], v[148:151], v[172:175], v[20:23]
	v_mfma_f32_16x16x32_bf16 v[16:19], v[156:159], v[172:175], v[16:19]
	v_mfma_f32_16x16x32_bf16 v[12:15], v[148:151], v[180:183], v[12:15]
	v_mfma_f32_16x16x32_bf16 v[8:11], v[156:159], v[180:183], v[8:11]
	v_mfma_f32_16x16x32_bf16 v[4:7], v[148:151], v[196:199], v[4:7]
	v_mfma_f32_16x16x32_bf16 v[0:3], v[156:159], v[196:199], v[0:3]
	s_setprio 1
	s_barrier
	s_add_i32 s19, 0, 0x18000
	s_add_i32 s40, 0, 0x1c000
	v_add_u32_e32 v140, s19, v233
	v_add_u32_e32 v156, s40, v233
	ds_read_b128 v[128:131], v140
	ds_read_b128 v[132:135], v140 offset:1024
	ds_read_b128 v[136:139], v140 offset:2048
	ds_read_b128 v[140:143], v140 offset:3072
	ds_read_b128 v[144:147], v156
	ds_read_b128 v[148:151], v156 offset:1024
	ds_read_b128 v[152:155], v156 offset:2048
	ds_read_b128 v[156:159], v156 offset:3072
	s_add_u32 s36, s36, 0x80000
	s_addc_u32 s37, s37, 0
	s_mov_b32 m0, s47
	v_lshl_add_u64 v[218:219], s[36:37], 0, v[200:201]
	ds_read_b128 v[160:163], v235 offset:32768
	ds_read_b128 v[164:167], v235 offset:33792
	ds_read_b128 v[168:171], v235 offset:34816
	ds_read_b128 v[172:175], v235 offset:35840
	ds_read_b128 v[176:179], v235 offset:36864
	ds_read_b128 v[180:183], v235 offset:37888
	ds_read_b128 v[188:191], v235 offset:38912
	ds_read_b128 v[196:199], v235 offset:39936
	global_load_lds_dwordx4 v[218:219], off
	v_lshl_add_u64 v[218:219], s[36:37], 0, v[202:203]
	s_mov_b32 m0, s48
	s_nop 0
	global_load_lds_dwordx4 v[218:219], off
	s_waitcnt vmcnt(8)
	s_waitcnt lgkmcnt(0)
	s_barrier
	s_setprio 0
	s_waitcnt lgkmcnt(0)
	v_mfma_f32_16x16x32_bf16 v[124:127], v[128:131], v[160:163], v[124:127]
	v_mfma_f32_16x16x32_bf16 v[120:123], v[136:139], v[160:163], v[120:123]
	v_mfma_f32_16x16x32_bf16 v[116:119], v[128:131], v[168:171], v[116:119]
	v_mfma_f32_16x16x32_bf16 v[112:115], v[136:139], v[168:171], v[112:115]
	v_mfma_f32_16x16x32_bf16 v[108:111], v[128:131], v[176:179], v[108:111]
	v_mfma_f32_16x16x32_bf16 v[104:107], v[136:139], v[176:179], v[104:107]
	v_mfma_f32_16x16x32_bf16 v[100:103], v[128:131], v[188:191], v[100:103]
	v_mfma_f32_16x16x32_bf16 v[96:99], v[136:139], v[188:191], v[96:99]
	v_mfma_f32_16x16x32_bf16 v[124:127], v[132:135], v[164:167], v[124:127]
	v_mfma_f32_16x16x32_bf16 v[120:123], v[140:143], v[164:167], v[120:123]
	v_mfma_f32_16x16x32_bf16 v[116:119], v[132:135], v[172:175], v[116:119]
	v_mfma_f32_16x16x32_bf16 v[112:115], v[140:143], v[172:175], v[112:115]
	v_mfma_f32_16x16x32_bf16 v[108:111], v[132:135], v[180:183], v[108:111]
	v_mfma_f32_16x16x32_bf16 v[104:107], v[140:143], v[180:183], v[104:107]
	v_mfma_f32_16x16x32_bf16 v[100:103], v[132:135], v[196:199], v[100:103]
	v_mfma_f32_16x16x32_bf16 v[96:99], v[140:143], v[196:199], v[96:99]
	v_mfma_f32_16x16x32_bf16 v[92:95], v[144:147], v[160:163], v[92:95]
	v_mfma_f32_16x16x32_bf16 v[88:91], v[152:155], v[160:163], v[88:91]
	v_mfma_f32_16x16x32_bf16 v[84:87], v[144:147], v[168:171], v[84:87]
	v_mfma_f32_16x16x32_bf16 v[80:83], v[152:155], v[168:171], v[80:83]
	v_mfma_f32_16x16x32_bf16 v[76:79], v[144:147], v[176:179], v[76:79]
	v_mfma_f32_16x16x32_bf16 v[72:75], v[152:155], v[176:179], v[72:75]
	v_mfma_f32_16x16x32_bf16 v[68:71], v[144:147], v[188:191], v[68:71]
	v_mfma_f32_16x16x32_bf16 v[64:67], v[152:155], v[188:191], v[64:67]
	v_mfma_f32_16x16x32_bf16 v[92:95], v[148:151], v[164:167], v[92:95]
	v_mfma_f32_16x16x32_bf16 v[88:91], v[156:159], v[164:167], v[88:91]
	v_mfma_f32_16x16x32_bf16 v[84:87], v[148:151], v[172:175], v[84:87]
	v_mfma_f32_16x16x32_bf16 v[80:83], v[156:159], v[172:175], v[80:83]
	v_mfma_f32_16x16x32_bf16 v[76:79], v[148:151], v[180:183], v[76:79]
	v_mfma_f32_16x16x32_bf16 v[72:75], v[156:159], v[180:183], v[72:75]
	v_mfma_f32_16x16x32_bf16 v[68:71], v[148:151], v[196:199], v[68:71]
	v_mfma_f32_16x16x32_bf16 v[64:67], v[156:159], v[196:199], v[64:67]
	s_setprio 1
	s_barrier
; #define PG8_STAGE(bufoff, gbase, voff) do { _Pragma("unroll") for (int _i = 0; _i < 2; ++_i) \
;         __builtin_amdgcn_global_load_lds((const unsigned*)((const char*)(gbase) + (voff)[_i]), (LAS unsigned*)(lds + (bufoff) + ldsw + _i * 8192), 16, 0, 0); } while (0)
; #define PG8_LDA(dst, b, h) do { _Pragma("unroll") for (int m = 0; m < 4; ++m) _Pragma("unroll") for (int k = 0; k < 2; ++k) dst[m][k] = *(const LAS bf16x8*)(lds + PG8_SA(b, h) + aoff + m * 2048 + k * 1024); } while (0)
; #define PG8_MMA(ai, bj, At, Bt) do { __builtin_amdgcn_s_setprio(1); _Pragma("unroll") for (int m = 0; m < 4; ++m) _Pragma("unroll") for (int n = 0; n < 2; ++n) _Pragma("unroll") for (int k = 0; k < 2; ++k) \
;         acc[ai][bj][m][n] = __builtin_amdgcn_mfma_f32_16x16x32_bf16(Bt[n][k], At[m][k], acc[ai][bj][m][n], 0, 0, 0); __builtin_amdgcn_s_setprio(0); } while (0)
; #define PG8_WAIT_V(n) asm volatile("s_waitcnt vmcnt(" #n ")" ::: "memory")
; #define PG8_WAIT_L(n) asm volatile("s_waitcnt lgkmcnt(" #n ")" ::: "memory")
; #define PG8_BAR __builtin_amdgcn_s_barrier()
; #define PG8_SCHED __builtin_amdgcn_sched_barrier(0)
; template <class Epi, class Sched>
; DI void gemm_phase(LAS unsigned char* lds, const int wv, const int lda, const int ldb, const Sched& S, const Epi& E) {
;     ...
;             PG8_LDA(At, 1, 1); PG8_STAGE(PG8_SB(1, 0), b3, voffB); PG8_STAGE(PG8_SB(1, 1), b3 + hstepB, voffB); PG8_STAGE(PG8_SA(1, 0), a3, voffA);
;             PG8_WAIT_V(8); PG8_WAIT_L(0); PG8_BAR; PG8_MMA(1, 0, At, B0); PG8_MMA(1, 1, At, B1); PG8_BAR; PG8_SCHED;
;         }
;         if (wr == 0) PG8_BAR;
	s_add_i32 s19, s19, s44
	v_lshl_add_u64 v[210:211], v[210:211], 0, s[28:29]
	s_mov_b32 m0, s19
	ds_read_b128 v[160:163], v235 offset:49152
	ds_read_b128 v[164:167], v235 offset:50176
	ds_read_b128 v[168:171], v235 offset:51200
	ds_read_b128 v[172:175], v235 offset:52224
	ds_read_b128 v[176:179], v235 offset:53248
	ds_read_b128 v[180:183], v235 offset:54272
	ds_read_b128 v[188:191], v235 offset:55296
	ds_read_b128 v[196:199], v235 offset:56320
	global_load_lds_dwordx4 v[210:211], off
	s_add_i32 m0, s19, 0x2000
	s_add_u32 s34, s34, 0x80080
	v_lshl_add_u64 v[210:211], v[212:213], 0, s[28:29]
	s_addc_u32 s35, s35, 0
	s_add_i32 s19, s40, s44
	global_load_lds_dwordx4 v[210:211], off
	v_lshl_add_u64 v[210:211], s[34:35], 0, v[184:185]
	s_mov_b32 m0, s19
	s_nop 0
	global_load_lds_dwordx4 v[210:211], off
	v_lshl_add_u64 v[210:211], s[34:35], 0, v[204:205]
	s_add_i32 m0, s19, 0x2000
	s_nop 0
	global_load_lds_dwordx4 v[210:211], off
	v_lshl_add_u64 v[210:211], v[214:215], 0, s[28:29]
	s_mov_b32 m0, s49
	s_nop 0
	global_load_lds_dwordx4 v[210:211], off
	v_lshl_add_u64 v[210:211], v[216:217], 0, s[28:29]
	s_mov_b32 m0, s50
	s_nop 0
	global_load_lds_dwordx4 v[210:211], off
	s_waitcnt vmcnt(8)
	s_waitcnt lgkmcnt(0)
	s_barrier
	s_setprio 0
	s_waitcnt lgkmcnt(0)
	v_mfma_f32_16x16x32_bf16 v[60:63], v[128:131], v[160:163], v[60:63]
	v_mfma_f32_16x16x32_bf16 v[56:59], v[136:139], v[160:163], v[56:59]
	v_mfma_f32_16x16x32_bf16 v[52:55], v[128:131], v[168:171], v[52:55]
	v_mfma_f32_16x16x32_bf16 v[48:51], v[136:139], v[168:171], v[48:51]
	v_mfma_f32_16x16x32_bf16 v[44:47], v[128:131], v[176:179], v[44:47]
	v_mfma_f32_16x16x32_bf16 v[40:43], v[136:139], v[176:179], v[40:43]
	v_mfma_f32_16x16x32_bf16 v[36:39], v[128:131], v[188:191], v[36:39]
	v_mfma_f32_16x16x32_bf16 v[32:35], v[136:139], v[188:191], v[32:35]
	v_mfma_f32_16x16x32_bf16 v[60:63], v[132:135], v[164:167], v[60:63]
	v_mfma_f32_16x16x32_bf16 v[56:59], v[140:143], v[164:167], v[56:59]
	v_mfma_f32_16x16x32_bf16 v[52:55], v[132:135], v[172:175], v[52:55]
	v_mfma_f32_16x16x32_bf16 v[48:51], v[140:143], v[172:175], v[48:51]
	v_mfma_f32_16x16x32_bf16 v[44:47], v[132:135], v[180:183], v[44:47]
	v_mfma_f32_16x16x32_bf16 v[40:43], v[140:143], v[180:183], v[40:43]
	v_mfma_f32_16x16x32_bf16 v[36:39], v[132:135], v[196:199], v[36:39]
	v_mfma_f32_16x16x32_bf16 v[32:35], v[140:143], v[196:199], v[32:35]
	v_mfma_f32_16x16x32_bf16 v[28:31], v[144:147], v[160:163], v[28:31]
	v_mfma_f32_16x16x32_bf16 v[24:27], v[152:155], v[160:163], v[24:27]
	v_mfma_f32_16x16x32_bf16 v[20:23], v[144:147], v[168:171], v[20:23]
	v_mfma_f32_16x16x32_bf16 v[16:19], v[152:155], v[168:171], v[16:19]
	v_mfma_f32_16x16x32_bf16 v[12:15], v[144:147], v[176:179], v[12:15]
	v_mfma_f32_16x16x32_bf16 v[8:11], v[152:155], v[176:179], v[8:11]
	v_mfma_f32_16x16x32_bf16 v[4:7], v[144:147], v[188:191], v[4:7]
	v_mfma_f32_16x16x32_bf16 v[0:3], v[152:155], v[188:191], v[0:3]
	v_mfma_f32_16x16x32_bf16 v[28:31], v[148:151], v[164:167], v[28:31]
	v_mfma_f32_16x16x32_bf16 v[24:27], v[156:159], v[164:167], v[24:27]
	v_mfma_f32_16x16x32_bf16 v[20:23], v[148:151], v[172:175], v[20:23]
	v_mfma_f32_16x16x32_bf16 v[16:19], v[156:159], v[172:175], v[16:19]
	v_mfma_f32_16x16x32_bf16 v[12:15], v[148:151], v[180:183], v[12:15]
	v_mfma_f32_16x16x32_bf16 v[8:11], v[156:159], v[180:183], v[8:11]
	v_mfma_f32_16x16x32_bf16 v[4:7], v[148:151], v[196:199], v[4:7]
	v_mfma_f32_16x16x32_bf16 v[0:3], v[156:159], v[196:199], v[0:3]
	s_setprio 1
	s_barrier
	s_add_u32 s6, s6, 0x100
	s_addc_u32 s7, s7, 0
	s_add_u32 s1, s1, 0x100
	s_addc_u32 s15, s15, 0
	s_cmp_ge_u32 s31, s27
	s_mov_b32 s19, s31
	s_cbranch_scc0 .LBB0_1185
	s_and_b64 vcc, exec, s[12:13]
	s_cbranch_vccz .LBB0_1188
	s_barrier

; #define PG8_STAGE(bufoff, gbase, voff) do { _Pragma("unroll") for (int _i = 0; _i < 2; ++_i) \
;         __builtin_amdgcn_global_load_lds((const unsigned*)((const char*)(gbase) + (voff)[_i]), (LAS unsigned*)(lds + (bufoff) + ldsw + _i * 8192), 16, 0, 0); } while (0)
; #define PG8_LDA(dst, b, h) do { _Pragma("unroll") for (int m = 0; m < 4; ++m) _Pragma("unroll") for (int k = 0; k < 2; ++k) dst[m][k] = *(const LAS bf16x8*)(lds + PG8_SA(b, h) + aoff + m * 2048 + k * 1024); } while (0)
; #define PG8_LDB(dst, b, h) do { _Pragma("unroll") for (int n = 0; n < 2; ++n) _Pragma("unroll") for (int k = 0; k < 2; ++k) dst[n][k] = *(const LAS bf16x8*)(lds + PG8_SB(b, h) + boff + n * 2048 + k * 1024); } while (0)
; #define PG8_MMA(ai, bj, At, Bt) do { __builtin_amdgcn_s_setprio(1); _Pragma("unroll") for (int m = 0; m < 4; ++m) _Pragma("unroll") for (int n = 0; n < 2; ++n) _Pragma("unroll") for (int k = 0; k < 2; ++k) \
;         acc[ai][bj][m][n] = __builtin_amdgcn_mfma_f32_16x16x32_bf16(Bt[n][k], At[m][k], acc[ai][bj][m][n], 0, 0, 0); __builtin_amdgcn_s_setprio(0); } while (0)
; #define PG8_WAIT_V(n) asm volatile("s_waitcnt vmcnt(" #n ")" ::: "memory")
; #define PG8_WAIT_L(n) asm volatile("s_waitcnt lgkmcnt(" #n ")" ::: "memory")
; #define PG8_BAR __builtin_amdgcn_s_barrier()
; #define PG8_SCHED __builtin_amdgcn_sched_barrier(0)
; template <class Epi, class Sched>
; DI void gemm_phase(LAS unsigned char* lds, const int wv, const int lda, const int ldb, const Sched& S, const Epi& E) {
;     ...
;             const bool last = (t == nt - 2);
;             const char* a1 = cA + (size_t)(t + 1) * kstep;
;             const char* a2 = last ? nA : cA + (size_t)(t + 2) * kstep; const char* b2 = last ? nB : cB + (size_t)(t + 2) * kstep;
;             const char* a3 = a2 + kstep; const char* b3 = b2 + kstep;
;             PG8_LDB(B0, 0, 0); PG8_LDB(B1, 0, 1); PG8_SCHED; PG8_LDA(At, 0, 0); PG8_STAGE(PG8_SA(1, 1), a1 + hstepA, voffA);
;             PG8_WAIT_V(8); PG8_WAIT_L(0); PG8_BAR; PG8_MMA(0, 0, At, B0); PG8_MMA(0, 1, At, B1); PG8_BAR; PG8_SCHED;
;             PG8_LDA(At, 0, 1); PG8_STAGE(PG8_SB(0, 0), b2, voffB); PG8_STAGE(PG8_SB(0, 1), b2 + hstepB, voffB); PG8_STAGE(PG8_SA(0, 0), a2, voffA);
;             PG8_WAIT_V(8); PG8_WAIT_L(0); PG8_BAR; PG8_MMA(1, 0, At, B0); PG8_MMA(1, 1, At, B1); PG8_BAR; PG8_SCHED;
.LBB0_1299:
	s_add_u32 s34, s30, 0xfff80080
	s_addc_u32 s35, s31, -1
	s_add_i32 s54, 0, 0x10000
	s_cmp_eq_u32 s53, 28
	s_cselect_b32 s37, s0, s35
	s_cselect_b32 s36, s1, s34
	s_cselect_b32 s35, s11, s52
	s_cselect_b32 s34, s15, s19
	s_add_i32 s56, 0, 0x14000
	v_add_u32_e32 v150, s54, v155
	v_add_u32_e32 v172, s56, v155
	ds_read_b128 v[128:131], v150
	ds_read_b128 v[142:145], v150 offset:1024
	ds_read_b128 v[146:149], v150 offset:2048
	ds_read_b128 v[150:153], v150 offset:3072
	ds_read_b128 v[160:163], v172
	ds_read_b128 v[164:167], v172 offset:1024
	ds_read_b128 v[168:171], v172 offset:2048
	ds_read_b128 v[172:175], v172 offset:3072
	v_lshl_add_u64 v[216:217], s[30:31], 0, v[138:139]
	s_add_i32 m0, s27, 0xc000
	ds_read_b128 v[176:179], v159
	ds_read_b128 v[180:183], v159 offset:1024
	ds_read_b128 v[188:191], v159 offset:2048
	ds_read_b128 v[196:199], v159 offset:3072
	ds_read_b128 v[200:203], v159 offset:4096
	ds_read_b128 v[204:207], v159 offset:5120
	ds_read_b128 v[208:211], v159 offset:6144
	ds_read_b128 v[212:215], v159 offset:7168
	global_load_lds_dwordx4 v[216:217], off
	v_lshl_add_u64 v[216:217], s[30:31], 0, v[140:141]
	s_add_i32 m0, s27, 0xe000
	s_nop 0
	global_load_lds_dwordx4 v[216:217], off
	s_waitcnt vmcnt(8)
	s_waitcnt lgkmcnt(0)
	s_barrier
	s_setprio 0
	s_waitcnt lgkmcnt(0)
	v_mfma_f32_16x16x32_bf16 v[124:127], v[128:131], v[176:179], v[124:127]
	v_mfma_f32_16x16x32_bf16 v[120:123], v[146:149], v[176:179], v[120:123]
	v_mfma_f32_16x16x32_bf16 v[108:111], v[128:131], v[188:191], v[108:111]
	v_mfma_f32_16x16x32_bf16 v[104:107], v[146:149], v[188:191], v[104:107]
	v_mfma_f32_16x16x32_bf16 v[96:99], v[128:131], v[200:203], v[96:99]
	v_mfma_f32_16x16x32_bf16 v[88:91], v[146:149], v[200:203], v[88:91]
	v_mfma_f32_16x16x32_bf16 v[80:83], v[128:131], v[208:211], v[80:83]
	v_mfma_f32_16x16x32_bf16 v[72:75], v[146:149], v[208:211], v[72:75]
	v_mfma_f32_16x16x32_bf16 v[124:127], v[142:145], v[180:183], v[124:127]
	v_mfma_f32_16x16x32_bf16 v[120:123], v[150:153], v[180:183], v[120:123]
	v_mfma_f32_16x16x32_bf16 v[108:111], v[142:145], v[196:199], v[108:111]
	v_mfma_f32_16x16x32_bf16 v[104:107], v[150:153], v[196:199], v[104:107]
	v_mfma_f32_16x16x32_bf16 v[96:99], v[142:145], v[204:207], v[96:99]
	v_mfma_f32_16x16x32_bf16 v[88:91], v[150:153], v[204:207], v[88:91]
	v_mfma_f32_16x16x32_bf16 v[80:83], v[142:145], v[212:215], v[80:83]
	v_mfma_f32_16x16x32_bf16 v[72:75], v[150:153], v[212:215], v[72:75]
	v_mfma_f32_16x16x32_bf16 v[116:119], v[160:163], v[176:179], v[116:119]
	v_mfma_f32_16x16x32_bf16 v[112:115], v[168:171], v[176:179], v[112:115]
	v_mfma_f32_16x16x32_bf16 v[100:103], v[160:163], v[188:191], v[100:103]
	v_mfma_f32_16x16x32_bf16 v[92:95], v[168:171], v[188:191], v[92:95]
	v_mfma_f32_16x16x32_bf16 v[84:87], v[160:163], v[200:203], v[84:87]
	v_mfma_f32_16x16x32_bf16 v[76:79], v[168:171], v[200:203], v[76:79]
	v_mfma_f32_16x16x32_bf16 v[68:71], v[160:163], v[208:211], v[68:71]
	v_mfma_f32_16x16x32_bf16 v[64:67], v[168:171], v[208:211], v[64:67]
	v_mfma_f32_16x16x32_bf16 v[116:119], v[164:167], v[180:183], v[116:119]
	v_mfma_f32_16x16x32_bf16 v[112:115], v[172:175], v[180:183], v[112:115]
	v_mfma_f32_16x16x32_bf16 v[100:103], v[164:167], v[196:199], v[100:103]
	v_mfma_f32_16x16x32_bf16 v[92:95], v[172:175], v[196:199], v[92:95]
	v_mfma_f32_16x16x32_bf16 v[84:87], v[164:167], v[204:207], v[84:87]
	v_mfma_f32_16x16x32_bf16 v[76:79], v[172:175], v[204:207], v[76:79]
	v_mfma_f32_16x16x32_bf16 v[68:71], v[164:167], v[212:215], v[68:71]
	v_mfma_f32_16x16x32_bf16 v[64:67], v[172:175], v[212:215], v[64:67]
	s_setprio 1
	s_barrier
	s_add_i32 s54, s54, s41
	v_lshl_add_u64 v[216:217], s[34:35], 0, v[184:185]
	s_mov_b32 m0, s54
	ds_read_b128 v[176:179], v159 offset:16384
	ds_read_b128 v[180:183], v159 offset:17408
	ds_read_b128 v[188:191], v159 offset:18432
	ds_read_b128 v[196:199], v159 offset:19456
	ds_read_b128 v[200:203], v159 offset:20480
	ds_read_b128 v[204:207], v159 offset:21504
	ds_read_b128 v[208:211], v159 offset:22528
	ds_read_b128 v[212:215], v159 offset:23552
	global_load_lds_dwordx4 v[216:217], off
	s_add_i32 m0, s54, 0x2000
	s_add_u32 s54, s34, 0x80000
	v_lshl_add_u64 v[218:219], s[34:35], 0, v[136:137]
	s_addc_u32 s55, s35, 0
	s_add_i32 s56, s56, s41
	global_load_lds_dwordx4 v[218:219], off
	v_lshl_add_u64 v[220:221], s[54:55], 0, v[184:185]
	s_mov_b32 m0, s56
	v_lshl_add_u64 v[222:223], s[36:37], 0, v[134:135]
	global_load_lds_dwordx4 v[220:221], off
	v_lshl_add_u64 v[220:221], s[54:55], 0, v[136:137]
	s_add_i32 m0, s56, 0x2000
	s_nop 0
	global_load_lds_dwordx4 v[220:221], off
	v_lshl_add_u64 v[220:221], s[36:37], 0, v[132:133]
	s_mov_b32 m0, s27
	s_nop 0
	global_load_lds_dwordx4 v[220:221], off
	s_mov_b32 m0, s42
	s_nop 0
	global_load_lds_dwordx4 v[222:223], off
	s_waitcnt vmcnt(8)
	s_waitcnt lgkmcnt(0)
	s_barrier
; #define PG8_STAGE(bufoff, gbase, voff) do { _Pragma("unroll") for (int _i = 0; _i < 2; ++_i) \
;         __builtin_amdgcn_global_load_lds((const unsigned*)((const char*)(gbase) + (voff)[_i]), (LAS unsigned*)(lds + (bufoff) + ldsw + _i * 8192), 16, 0, 0); } while (0)
; #define PG8_LDA(dst, b, h) do { _Pragma("unroll") for (int m = 0; m < 4; ++m) _Pragma("unroll") for (int k = 0; k < 2; ++k) dst[m][k] = *(const LAS bf16x8*)(lds + PG8_SA(b, h) + aoff + m * 2048 + k * 1024); } while (0)
; #define PG8_LDB(dst, b, h) do { _Pragma("unroll") for (int n = 0; n < 2; ++n) _Pragma("unroll") for (int k = 0; k < 2; ++k) dst[n][k] = *(const LAS bf16x8*)(lds + PG8_SB(b, h) + boff + n * 2048 + k * 1024); } while (0)
; #define PG8_MMA(ai, bj, At, Bt) do { __builtin_amdgcn_s_setprio(1); _Pragma("unroll") for (int m = 0; m < 4; ++m) _Pragma("unroll") for (int n = 0; n < 2; ++n) _Pragma("unroll") for (int k = 0; k < 2; ++k) \
;         acc[ai][bj][m][n] = __builtin_amdgcn_mfma_f32_16x16x32_bf16(Bt[n][k], At[m][k], acc[ai][bj][m][n], 0, 0, 0); __builtin_amdgcn_s_setprio(0); } while (0)
; #define PG8_WAIT_V(n) asm volatile("s_waitcnt vmcnt(" #n ")" ::: "memory")
; #define PG8_WAIT_L(n) asm volatile("s_waitcnt lgkmcnt(" #n ")" ::: "memory")
; #define PG8_BAR __builtin_amdgcn_s_barrier()
; #define PG8_SCHED __builtin_amdgcn_sched_barrier(0)
; template <class Epi, class Sched>
; DI void gemm_phase(LAS unsigned char* lds, const int wv, const int lda, const int ldb, const Sched& S, const Epi& E) {
;     ...
;             PG8_WAIT_V(8); PG8_WAIT_L(0); PG8_BAR; PG8_MMA(1, 0, At, B0); PG8_MMA(1, 1, At, B1); PG8_BAR; PG8_SCHED;
;             PG8_LDB(B0, 1, 0); PG8_LDB(B1, 1, 1); PG8_SCHED; PG8_LDA(At, 1, 0); PG8_STAGE(PG8_SA(0, 1), a2 + hstepA, voffA);
;             PG8_WAIT_V(8); PG8_WAIT_L(0); PG8_BAR; PG8_MMA(0, 0, At, B0); PG8_MMA(0, 1, At, B1); PG8_BAR; PG8_SCHED;
	s_setprio 0
	s_waitcnt lgkmcnt(0)
	v_mfma_f32_16x16x32_bf16 v[60:63], v[128:131], v[176:179], v[60:63]
	v_mfma_f32_16x16x32_bf16 v[56:59], v[146:149], v[176:179], v[56:59]
	v_mfma_f32_16x16x32_bf16 v[48:51], v[128:131], v[188:191], v[48:51]
	v_mfma_f32_16x16x32_bf16 v[40:43], v[146:149], v[188:191], v[40:43]
	v_mfma_f32_16x16x32_bf16 v[32:35], v[128:131], v[200:203], v[32:35]
	v_mfma_f32_16x16x32_bf16 v[24:27], v[146:149], v[200:203], v[24:27]
	v_mfma_f32_16x16x32_bf16 v[16:19], v[128:131], v[208:211], v[16:19]
	v_mfma_f32_16x16x32_bf16 v[8:11], v[146:149], v[208:211], v[8:11]
	v_mfma_f32_16x16x32_bf16 v[60:63], v[142:145], v[180:183], v[60:63]
	v_mfma_f32_16x16x32_bf16 v[56:59], v[150:153], v[180:183], v[56:59]
	v_mfma_f32_16x16x32_bf16 v[48:51], v[142:145], v[196:199], v[48:51]
	v_mfma_f32_16x16x32_bf16 v[40:43], v[150:153], v[196:199], v[40:43]
	v_mfma_f32_16x16x32_bf16 v[32:35], v[142:145], v[204:207], v[32:35]
	v_mfma_f32_16x16x32_bf16 v[24:27], v[150:153], v[204:207], v[24:27]
	v_mfma_f32_16x16x32_bf16 v[16:19], v[142:145], v[212:215], v[16:19]
	v_mfma_f32_16x16x32_bf16 v[8:11], v[150:153], v[212:215], v[8:11]
	v_mfma_f32_16x16x32_bf16 v[52:55], v[160:163], v[176:179], v[52:55]
	v_mfma_f32_16x16x32_bf16 v[44:47], v[168:171], v[176:179], v[44:47]
	v_mfma_f32_16x16x32_bf16 v[36:39], v[160:163], v[188:191], v[36:39]
	v_mfma_f32_16x16x32_bf16 v[28:31], v[168:171], v[188:191], v[28:31]
	v_mfma_f32_16x16x32_bf16 v[20:23], v[160:163], v[200:203], v[20:23]
	v_mfma_f32_16x16x32_bf16 v[12:15], v[168:171], v[200:203], v[12:15]
	v_mfma_f32_16x16x32_bf16 v[4:7], v[160:163], v[208:211], v[4:7]
	v_mfma_f32_16x16x32_bf16 v[0:3], v[168:171], v[208:211], v[0:3]
	v_mfma_f32_16x16x32_bf16 v[52:55], v[164:167], v[180:183], v[52:55]
	v_mfma_f32_16x16x32_bf16 v[44:47], v[172:175], v[180:183], v[44:47]
	v_mfma_f32_16x16x32_bf16 v[36:39], v[164:167], v[196:199], v[36:39]
	v_mfma_f32_16x16x32_bf16 v[28:31], v[172:175], v[196:199], v[28:31]
	v_mfma_f32_16x16x32_bf16 v[20:23], v[164:167], v[204:207], v[20:23]
	v_mfma_f32_16x16x32_bf16 v[12:15], v[172:175], v[204:207], v[12:15]
	v_mfma_f32_16x16x32_bf16 v[4:7], v[164:167], v[212:215], v[4:7]
	v_mfma_f32_16x16x32_bf16 v[0:3], v[172:175], v[212:215], v[0:3]
	s_setprio 1
	s_barrier
	s_add_i32 s54, 0, 0x18000
	s_add_i32 s55, 0, 0x1c000
	v_add_u32_e32 v150, s54, v155
	v_add_u32_e32 v172, s55, v155
	ds_read_b128 v[128:131], v150
	ds_read_b128 v[142:145], v150 offset:1024
	ds_read_b128 v[146:149], v150 offset:2048
	ds_read_b128 v[150:153], v150 offset:3072
	ds_read_b128 v[160:163], v172
	ds_read_b128 v[164:167], v172 offset:1024
	ds_read_b128 v[168:171], v172 offset:2048
	ds_read_b128 v[172:175], v172 offset:3072
	s_add_u32 s36, s36, 0x80000
	s_addc_u32 s37, s37, 0
	s_mov_b32 m0, s43
	v_lshl_add_u64 v[234:235], s[36:37], 0, v[132:133]
	ds_read_b128 v[176:179], v159 offset:32768
	ds_read_b128 v[180:183], v159 offset:33792
	ds_read_b128 v[188:191], v159 offset:34816
	ds_read_b128 v[196:199], v159 offset:35840
	ds_read_b128 v[200:203], v159 offset:36864
	ds_read_b128 v[204:207], v159 offset:37888
	ds_read_b128 v[208:211], v159 offset:38912
	ds_read_b128 v[212:215], v159 offset:39936
	global_load_lds_dwordx4 v[234:235], off
	v_lshl_add_u64 v[234:235], s[36:37], 0, v[134:135]
	s_mov_b32 m0, s44
	s_nop 0
	global_load_lds_dwordx4 v[234:235], off
	s_waitcnt vmcnt(8)
	s_waitcnt lgkmcnt(0)
	s_barrier
	s_setprio 0
	s_waitcnt lgkmcnt(0)
	v_mfma_f32_16x16x32_bf16 v[124:127], v[128:131], v[176:179], v[124:127]
	v_mfma_f32_16x16x32_bf16 v[120:123], v[146:149], v[176:179], v[120:123]
	v_mfma_f32_16x16x32_bf16 v[108:111], v[128:131], v[188:191], v[108:111]
	v_mfma_f32_16x16x32_bf16 v[104:107], v[146:149], v[188:191], v[104:107]
	v_mfma_f32_16x16x32_bf16 v[96:99], v[128:131], v[200:203], v[96:99]
	v_mfma_f32_16x16x32_bf16 v[88:91], v[146:149], v[200:203], v[88:91]
	v_mfma_f32_16x16x32_bf16 v[80:83], v[128:131], v[208:211], v[80:83]
	v_mfma_f32_16x16x32_bf16 v[72:75], v[146:149], v[208:211], v[72:75]
	v_mfma_f32_16x16x32_bf16 v[124:127], v[142:145], v[180:183], v[124:127]
	v_mfma_f32_16x16x32_bf16 v[120:123], v[150:153], v[180:183], v[120:123]
	v_mfma_f32_16x16x32_bf16 v[108:111], v[142:145], v[196:199], v[108:111]
	v_mfma_f32_16x16x32_bf16 v[104:107], v[150:153], v[196:199], v[104:107]
	v_mfma_f32_16x16x32_bf16 v[96:99], v[142:145], v[204:207], v[96:99]
	v_mfma_f32_16x16x32_bf16 v[88:91], v[150:153], v[204:207], v[88:91]
	v_mfma_f32_16x16x32_bf16 v[80:83], v[142:145], v[212:215], v[80:83]
	v_mfma_f32_16x16x32_bf16 v[72:75], v[150:153], v[212:215], v[72:75]
	v_mfma_f32_16x16x32_bf16 v[116:119], v[160:163], v[176:179], v[116:119]
	v_mfma_f32_16x16x32_bf16 v[112:115], v[168:171], v[176:179], v[112:115]
	v_mfma_f32_16x16x32_bf16 v[100:103], v[160:163], v[188:191], v[100:103]
	v_mfma_f32_16x16x32_bf16 v[92:95], v[168:171], v[188:191], v[92:95]
	v_mfma_f32_16x16x32_bf16 v[84:87], v[160:163], v[200:203], v[84:87]
	v_mfma_f32_16x16x32_bf16 v[76:79], v[168:171], v[200:203], v[76:79]
	v_mfma_f32_16x16x32_bf16 v[68:71], v[160:163], v[208:211], v[68:71]
	v_mfma_f32_16x16x32_bf16 v[64:67], v[168:171], v[208:211], v[64:67]
	v_mfma_f32_16x16x32_bf16 v[116:119], v[164:167], v[180:183], v[116:119]
	v_mfma_f32_16x16x32_bf16 v[112:115], v[172:175], v[180:183], v[112:115]
	v_mfma_f32_16x16x32_bf16 v[100:103], v[164:167], v[196:199], v[100:103]
	v_mfma_f32_16x16x32_bf16 v[92:95], v[172:175], v[196:199], v[92:95]
	v_mfma_f32_16x16x32_bf16 v[84:87], v[164:167], v[204:207], v[84:87]
	v_mfma_f32_16x16x32_bf16 v[76:79], v[172:175], v[204:207], v[76:79]
	v_mfma_f32_16x16x32_bf16 v[68:71], v[164:167], v[212:215], v[68:71]
	v_mfma_f32_16x16x32_bf16 v[64:67], v[172:175], v[212:215], v[64:67]
	s_setprio 1
	s_barrier
; #define PG8_STAGE(bufoff, gbase, voff) do { _Pragma("unroll") for (int _i = 0; _i < 2; ++_i) \
;         __builtin_amdgcn_global_load_lds((const unsigned*)((const char*)(gbase) + (voff)[_i]), (LAS unsigned*)(lds + (bufoff) + ldsw + _i * 8192), 16, 0, 0); } while (0)
; #define PG8_LDA(dst, b, h) do { _Pragma("unroll") for (int m = 0; m < 4; ++m) _Pragma("unroll") for (int k = 0; k < 2; ++k) dst[m][k] = *(const LAS bf16x8*)(lds + PG8_SA(b, h) + aoff + m * 2048 + k * 1024); } while (0)
; #define PG8_MMA(ai, bj, At, Bt) do { __builtin_amdgcn_s_setprio(1); _Pragma("unroll") for (int m = 0; m < 4; ++m) _Pragma("unroll") for (int n = 0; n < 2; ++n) _Pragma("unroll") for (int k = 0; k < 2; ++k) \
;         acc[ai][bj][m][n] = __builtin_amdgcn_mfma_f32_16x16x32_bf16(Bt[n][k], At[m][k], acc[ai][bj][m][n], 0, 0, 0); __builtin_amdgcn_s_setprio(0); } while (0)
; #define PG8_WAIT_V(n) asm volatile("s_waitcnt vmcnt(" #n ")" ::: "memory")
; #define PG8_WAIT_L(n) asm volatile("s_waitcnt lgkmcnt(" #n ")" ::: "memory")
; #define PG8_BAR __builtin_amdgcn_s_barrier()
; #define PG8_SCHED __builtin_amdgcn_sched_barrier(0)
; template <class Epi, class Sched>
; DI void gemm_phase(LAS unsigned char* lds, const int wv, const int lda, const int ldb, const Sched& S, const Epi& E) {
;     ...
;             PG8_LDA(At, 1, 1); PG8_STAGE(PG8_SB(1, 0), b3, voffB); PG8_STAGE(PG8_SB(1, 1), b3 + hstepB, voffB); PG8_STAGE(PG8_SA(1, 0), a3, voffA);
;             PG8_WAIT_V(8); PG8_WAIT_L(0); PG8_BAR; PG8_MMA(1, 0, At, B0); PG8_MMA(1, 1, At, B1); PG8_BAR; PG8_SCHED;
;         }
;         if (wr == 0) PG8_BAR;
	s_add_i32 s36, s54, s41
	v_lshl_add_u64 v[216:217], v[216:217], 0, s[28:29]
	s_mov_b32 m0, s36
	ds_read_b128 v[176:179], v159 offset:49152
	ds_read_b128 v[180:183], v159 offset:50176
	ds_read_b128 v[188:191], v159 offset:51200
	ds_read_b128 v[196:199], v159 offset:52224
	ds_read_b128 v[200:203], v159 offset:53248
	ds_read_b128 v[204:207], v159 offset:54272
	ds_read_b128 v[208:211], v159 offset:55296
	ds_read_b128 v[212:215], v159 offset:56320
	global_load_lds_dwordx4 v[216:217], off
	s_add_i32 m0, s36, 0x2000
	s_add_u32 s34, s34, 0x80080
	v_lshl_add_u64 v[216:217], v[218:219], 0, s[28:29]
	s_addc_u32 s35, s35, 0
	s_add_i32 s36, s55, s41
	global_load_lds_dwordx4 v[216:217], off
	v_lshl_add_u64 v[216:217], s[34:35], 0, v[184:185]
	s_mov_b32 m0, s36
	s_nop 0
	global_load_lds_dwordx4 v[216:217], off
	v_lshl_add_u64 v[216:217], s[34:35], 0, v[136:137]
	s_add_i32 m0, s36, 0x2000
	s_nop 0
	global_load_lds_dwordx4 v[216:217], off
	v_lshl_add_u64 v[216:217], v[220:221], 0, s[28:29]
	s_mov_b32 m0, s45
	s_nop 0
	global_load_lds_dwordx4 v[216:217], off
	v_lshl_add_u64 v[216:217], v[222:223], 0, s[28:29]
	s_mov_b32 m0, s46
	s_nop 0
	global_load_lds_dwordx4 v[216:217], off
	s_waitcnt vmcnt(8)
	s_waitcnt lgkmcnt(0)
	s_barrier
	s_setprio 0
	s_waitcnt lgkmcnt(0)
	v_mfma_f32_16x16x32_bf16 v[60:63], v[128:131], v[176:179], v[60:63]
	v_mfma_f32_16x16x32_bf16 v[56:59], v[146:149], v[176:179], v[56:59]
	v_mfma_f32_16x16x32_bf16 v[48:51], v[128:131], v[188:191], v[48:51]
	v_mfma_f32_16x16x32_bf16 v[40:43], v[146:149], v[188:191], v[40:43]
	v_mfma_f32_16x16x32_bf16 v[32:35], v[128:131], v[200:203], v[32:35]
	v_mfma_f32_16x16x32_bf16 v[24:27], v[146:149], v[200:203], v[24:27]
	v_mfma_f32_16x16x32_bf16 v[16:19], v[128:131], v[208:211], v[16:19]
	v_mfma_f32_16x16x32_bf16 v[8:11], v[146:149], v[208:211], v[8:11]
	v_mfma_f32_16x16x32_bf16 v[60:63], v[142:145], v[180:183], v[60:63]
	v_mfma_f32_16x16x32_bf16 v[56:59], v[150:153], v[180:183], v[56:59]
	v_mfma_f32_16x16x32_bf16 v[48:51], v[142:145], v[196:199], v[48:51]
	v_mfma_f32_16x16x32_bf16 v[40:43], v[150:153], v[196:199], v[40:43]
	v_mfma_f32_16x16x32_bf16 v[32:35], v[142:145], v[204:207], v[32:35]
	v_mfma_f32_16x16x32_bf16 v[24:27], v[150:153], v[204:207], v[24:27]
	v_mfma_f32_16x16x32_bf16 v[16:19], v[142:145], v[212:215], v[16:19]
	v_mfma_f32_16x16x32_bf16 v[8:11], v[150:153], v[212:215], v[8:11]
	v_mfma_f32_16x16x32_bf16 v[52:55], v[160:163], v[176:179], v[52:55]
	v_mfma_f32_16x16x32_bf16 v[44:47], v[168:171], v[176:179], v[44:47]
	v_mfma_f32_16x16x32_bf16 v[36:39], v[160:163], v[188:191], v[36:39]
	v_mfma_f32_16x16x32_bf16 v[28:31], v[168:171], v[188:191], v[28:31]
	v_mfma_f32_16x16x32_bf16 v[20:23], v[160:163], v[200:203], v[20:23]
	v_mfma_f32_16x16x32_bf16 v[12:15], v[168:171], v[200:203], v[12:15]
	v_mfma_f32_16x16x32_bf16 v[4:7], v[160:163], v[208:211], v[4:7]
	v_mfma_f32_16x16x32_bf16 v[0:3], v[168:171], v[208:211], v[0:3]
	v_mfma_f32_16x16x32_bf16 v[52:55], v[164:167], v[180:183], v[52:55]
	v_mfma_f32_16x16x32_bf16 v[44:47], v[172:175], v[180:183], v[44:47]
	v_mfma_f32_16x16x32_bf16 v[36:39], v[164:167], v[196:199], v[36:39]
	v_mfma_f32_16x16x32_bf16 v[28:31], v[172:175], v[196:199], v[28:31]
	v_mfma_f32_16x16x32_bf16 v[20:23], v[164:167], v[204:207], v[20:23]
	v_mfma_f32_16x16x32_bf16 v[12:15], v[172:175], v[204:207], v[12:15]
	v_mfma_f32_16x16x32_bf16 v[4:7], v[164:167], v[212:215], v[4:7]
	v_mfma_f32_16x16x32_bf16 v[0:3], v[172:175], v[212:215], v[0:3]
	s_setprio 1
	s_barrier
	s_add_i32 s53, s53, 2
	s_add_u32 s30, s30, 0x100
	s_addc_u32 s31, s31, 0
	s_add_u32 s19, s19, 0x100
	s_addc_u32 s52, s52, 0
	s_cmp_gt_u32 s53, 29
	s_cbranch_scc0 .LBB0_1299
	s_and_b64 vcc, exec, s[12:13]
	s_cbranch_vccz .LBB0_1302
	s_barrier

; #define PG8_STAGE(bufoff, gbase, voff) do { _Pragma("unroll") for (int _i = 0; _i < 2; ++_i) \
;         __builtin_amdgcn_global_load_lds((const unsigned*)((const char*)(gbase) + (voff)[_i]), (LAS unsigned*)(lds + (bufoff) + ldsw + _i * 8192), 16, 0, 0); } while (0)
; #define PG8_LDA(dst, b, h) do { _Pragma("unroll") for (int m = 0; m < 4; ++m) _Pragma("unroll") for (int k = 0; k < 2; ++k) dst[m][k] = *(const LAS bf16x8*)(lds + PG8_SA(b, h) + aoff + m * 2048 + k * 1024); } while (0)
; #define PG8_LDB(dst, b, h) do { _Pragma("unroll") for (int n = 0; n < 2; ++n) _Pragma("unroll") for (int k = 0; k < 2; ++k) dst[n][k] = *(const LAS bf16x8*)(lds + PG8_SB(b, h) + boff + n * 2048 + k * 1024); } while (0)
; #define PG8_MMA(ai, bj, At, Bt) do { __builtin_amdgcn_s_setprio(1); _Pragma("unroll") for (int m = 0; m < 4; ++m) _Pragma("unroll") for (int n = 0; n < 2; ++n) _Pragma("unroll") for (int k = 0; k < 2; ++k) \
;         acc[ai][bj][m][n] = __builtin_amdgcn_mfma_f32_16x16x32_bf16(Bt[n][k], At[m][k], acc[ai][bj][m][n], 0, 0, 0); __builtin_amdgcn_s_setprio(0); } while (0)
; #define PG8_WAIT_V(n) asm volatile("s_waitcnt vmcnt(" #n ")" ::: "memory")
; #define PG8_WAIT_L(n) asm volatile("s_waitcnt lgkmcnt(" #n ")" ::: "memory")
; #define PG8_BAR __builtin_amdgcn_s_barrier()
; #define PG8_SCHED __builtin_amdgcn_sched_barrier(0)
; template <class Epi, class Sched>
; DI void gemm_phase(LAS unsigned char* lds, const int wv, const int lda, const int ldb, const Sched& S, const Epi& E) {
;     ...
;             const bool last = (t == nt - 2);
;             const char* a1 = cA + (size_t)(t + 1) * kstep;
;             const char* a2 = last ? nA : cA + (size_t)(t + 2) * kstep; const char* b2 = last ? nB : cB + (size_t)(t + 2) * kstep;
;             const char* a3 = a2 + kstep; const char* b3 = b2 + kstep;
;             PG8_LDB(B0, 0, 0); PG8_LDB(B1, 0, 1); PG8_SCHED; PG8_LDA(At, 0, 0); PG8_STAGE(PG8_SA(1, 1), a1 + hstepA, voffA);
;             PG8_WAIT_V(8); PG8_WAIT_L(0); PG8_BAR; PG8_MMA(0, 0, At, B0); PG8_MMA(0, 1, At, B1); PG8_BAR; PG8_SCHED;
;             PG8_LDA(At, 0, 1); PG8_STAGE(PG8_SB(0, 0), b2, voffB); PG8_STAGE(PG8_SB(0, 1), b2 + hstepB, voffB); PG8_STAGE(PG8_SA(0, 0), a2, voffA);
;             PG8_WAIT_V(8); PG8_WAIT_L(0); PG8_BAR; PG8_MMA(1, 0, At, B0); PG8_MMA(1, 1, At, B1); PG8_BAR; PG8_SCHED;
.LBB0_1397:
	s_add_u32 s30, s26, 0xfff80080
	s_addc_u32 s31, s27, -1
	s_add_i32 s51, 0, 0x10000
	s_cmp_eq_u32 s50, 28
	s_cselect_b32 s35, s0, s31
	s_cselect_b32 s34, s1, s30
	v_add_u32_e32 v142, s51, v145
	s_cselect_b32 s31, s13, s49
	s_cselect_b32 s30, s15, s48
	s_add_i32 s54, 0, 0x14000
	ds_read_b128 v[138:141], v142
	ds_read_b128 v[148:151], v142 offset:1024
	ds_read_b128 v[152:155], v142 offset:2048
	ds_read_b128 v[156:159], v142 offset:3072
	v_add_u32_e32 v142, s54, v145
	ds_read_b128 v[160:163], v142
	ds_read_b128 v[164:167], v142 offset:1024
	ds_read_b128 v[168:171], v142 offset:2048
	ds_read_b128 v[172:175], v142 offset:3072
	v_lshl_add_u64 v[142:143], s[26:27], 0, v[134:135]
	s_add_i32 m0, s25, 0xc000
	ds_read_b128 v[176:179], v147
	ds_read_b128 v[180:183], v147 offset:1024
	ds_read_b128 v[188:191], v147 offset:2048
	ds_read_b128 v[196:199], v147 offset:3072
	ds_read_b128 v[200:203], v147 offset:4096
	ds_read_b128 v[204:207], v147 offset:5120
	ds_read_b128 v[208:211], v147 offset:6144
	ds_read_b128 v[212:215], v147 offset:7168
	global_load_lds_dwordx4 v[142:143], off
	v_lshl_add_u64 v[142:143], s[26:27], 0, v[136:137]
	s_add_i32 m0, s25, 0xe000
	s_nop 0
	global_load_lds_dwordx4 v[142:143], off
	s_waitcnt vmcnt(8)
	s_waitcnt lgkmcnt(0)
	s_barrier
	s_setprio 0
	s_waitcnt lgkmcnt(0)
	v_mfma_f32_16x16x32_bf16 v[124:127], v[138:141], v[176:179], v[124:127]
	v_mfma_f32_16x16x32_bf16 v[120:123], v[152:155], v[176:179], v[120:123]
	v_mfma_f32_16x16x32_bf16 v[108:111], v[138:141], v[188:191], v[108:111]
	v_mfma_f32_16x16x32_bf16 v[104:107], v[152:155], v[188:191], v[104:107]
	v_mfma_f32_16x16x32_bf16 v[92:95], v[138:141], v[200:203], v[92:95]
	v_mfma_f32_16x16x32_bf16 v[88:91], v[152:155], v[200:203], v[88:91]
	v_mfma_f32_16x16x32_bf16 v[76:79], v[138:141], v[208:211], v[76:79]
	v_mfma_f32_16x16x32_bf16 v[72:75], v[152:155], v[208:211], v[72:75]
	v_mfma_f32_16x16x32_bf16 v[124:127], v[148:151], v[180:183], v[124:127]
	v_mfma_f32_16x16x32_bf16 v[120:123], v[156:159], v[180:183], v[120:123]
	v_mfma_f32_16x16x32_bf16 v[108:111], v[148:151], v[196:199], v[108:111]
	v_mfma_f32_16x16x32_bf16 v[104:107], v[156:159], v[196:199], v[104:107]
	v_mfma_f32_16x16x32_bf16 v[92:95], v[148:151], v[204:207], v[92:95]
	v_mfma_f32_16x16x32_bf16 v[88:91], v[156:159], v[204:207], v[88:91]
	v_mfma_f32_16x16x32_bf16 v[76:79], v[148:151], v[212:215], v[76:79]
	v_mfma_f32_16x16x32_bf16 v[72:75], v[156:159], v[212:215], v[72:75]
	v_mfma_f32_16x16x32_bf16 v[116:119], v[160:163], v[176:179], v[116:119]
	v_mfma_f32_16x16x32_bf16 v[112:115], v[168:171], v[176:179], v[112:115]
	v_mfma_f32_16x16x32_bf16 v[100:103], v[160:163], v[188:191], v[100:103]
	v_mfma_f32_16x16x32_bf16 v[96:99], v[168:171], v[188:191], v[96:99]
	v_mfma_f32_16x16x32_bf16 v[84:87], v[160:163], v[200:203], v[84:87]
	v_mfma_f32_16x16x32_bf16 v[80:83], v[168:171], v[200:203], v[80:83]
	v_mfma_f32_16x16x32_bf16 v[68:71], v[160:163], v[208:211], v[68:71]
	v_mfma_f32_16x16x32_bf16 v[64:67], v[168:171], v[208:211], v[64:67]
	v_mfma_f32_16x16x32_bf16 v[116:119], v[164:167], v[180:183], v[116:119]
	v_mfma_f32_16x16x32_bf16 v[112:115], v[172:175], v[180:183], v[112:115]
	v_mfma_f32_16x16x32_bf16 v[100:103], v[164:167], v[196:199], v[100:103]
	v_mfma_f32_16x16x32_bf16 v[96:99], v[172:175], v[196:199], v[96:99]
	v_mfma_f32_16x16x32_bf16 v[84:87], v[164:167], v[204:207], v[84:87]
	v_mfma_f32_16x16x32_bf16 v[80:83], v[172:175], v[204:207], v[80:83]
	v_mfma_f32_16x16x32_bf16 v[68:71], v[164:167], v[212:215], v[68:71]
	v_mfma_f32_16x16x32_bf16 v[64:67], v[172:175], v[212:215], v[64:67]
	s_setprio 1
	s_barrier
	s_add_i32 s51, s51, s38
	v_lshl_add_u64 v[142:143], s[30:31], 0, v[184:185]
	s_mov_b32 m0, s51
	ds_read_b128 v[176:179], v147 offset:16384
	ds_read_b128 v[180:183], v147 offset:17408
	ds_read_b128 v[188:191], v147 offset:18432
	ds_read_b128 v[196:199], v147 offset:19456
	ds_read_b128 v[200:203], v147 offset:20480
	ds_read_b128 v[204:207], v147 offset:21504
	ds_read_b128 v[208:211], v147 offset:22528
	ds_read_b128 v[212:215], v147 offset:23552
	global_load_lds_dwordx4 v[142:143], off
	s_add_i32 m0, s51, 0x2000
	s_add_u32 s52, s30, 0x80000
	v_lshl_add_u64 v[216:217], s[30:31], 0, v[132:133]
	s_addc_u32 s53, s31, 0
	s_add_i32 s51, s54, s38
	global_load_lds_dwordx4 v[216:217], off
	v_lshl_add_u64 v[218:219], s[52:53], 0, v[184:185]
	s_mov_b32 m0, s51
	v_lshl_add_u64 v[220:221], s[34:35], 0, v[130:131]
	global_load_lds_dwordx4 v[218:219], off
	v_lshl_add_u64 v[218:219], s[52:53], 0, v[132:133]
	s_add_i32 m0, s51, 0x2000
	s_nop 0
	global_load_lds_dwordx4 v[218:219], off
	v_lshl_add_u64 v[218:219], s[34:35], 0, v[128:129]
	s_mov_b32 m0, s25
	s_nop 0
	global_load_lds_dwordx4 v[218:219], off
	s_mov_b32 m0, s39
	s_nop 0
	global_load_lds_dwordx4 v[220:221], off
	s_waitcnt vmcnt(8)
	s_waitcnt lgkmcnt(0)
	s_barrier
; #define PG8_STAGE(bufoff, gbase, voff) do { _Pragma("unroll") for (int _i = 0; _i < 2; ++_i) \
;         __builtin_amdgcn_global_load_lds((const unsigned*)((const char*)(gbase) + (voff)[_i]), (LAS unsigned*)(lds + (bufoff) + ldsw + _i * 8192), 16, 0, 0); } while (0)
; #define PG8_LDA(dst, b, h) do { _Pragma("unroll") for (int m = 0; m < 4; ++m) _Pragma("unroll") for (int k = 0; k < 2; ++k) dst[m][k] = *(const LAS bf16x8*)(lds + PG8_SA(b, h) + aoff + m * 2048 + k * 1024); } while (0)
; #define PG8_LDB(dst, b, h) do { _Pragma("unroll") for (int n = 0; n < 2; ++n) _Pragma("unroll") for (int k = 0; k < 2; ++k) dst[n][k] = *(const LAS bf16x8*)(lds + PG8_SB(b, h) + boff + n * 2048 + k * 1024); } while (0)
; #define PG8_MMA(ai, bj, At, Bt) do { __builtin_amdgcn_s_setprio(1); _Pragma("unroll") for (int m = 0; m < 4; ++m) _Pragma("unroll") for (int n = 0; n < 2; ++n) _Pragma("unroll") for (int k = 0; k < 2; ++k) \
;         acc[ai][bj][m][n] = __builtin_amdgcn_mfma_f32_16x16x32_bf16(Bt[n][k], At[m][k], acc[ai][bj][m][n], 0, 0, 0); __builtin_amdgcn_s_setprio(0); } while (0)
; #define PG8_WAIT_V(n) asm volatile("s_waitcnt vmcnt(" #n ")" ::: "memory")
; #define PG8_WAIT_L(n) asm volatile("s_waitcnt lgkmcnt(" #n ")" ::: "memory")
; #define PG8_BAR __builtin_amdgcn_s_barrier()
; #define PG8_SCHED __builtin_amdgcn_sched_barrier(0)
; template <class Epi, class Sched>
; DI void gemm_phase(LAS unsigned char* lds, const int wv, const int lda, const int ldb, const Sched& S, const Epi& E) {
;     ...
;             PG8_WAIT_V(8); PG8_WAIT_L(0); PG8_BAR; PG8_MMA(1, 0, At, B0); PG8_MMA(1, 1, At, B1); PG8_BAR; PG8_SCHED;
;             PG8_LDB(B0, 1, 0); PG8_LDB(B1, 1, 1); PG8_SCHED; PG8_LDA(At, 1, 0); PG8_STAGE(PG8_SA(0, 1), a2 + hstepA, voffA);
;             PG8_WAIT_V(8); PG8_WAIT_L(0); PG8_BAR; PG8_MMA(0, 0, At, B0); PG8_MMA(0, 1, At, B1); PG8_BAR; PG8_SCHED;
	s_setprio 0
	s_waitcnt lgkmcnt(0)
	v_mfma_f32_16x16x32_bf16 v[60:63], v[138:141], v[176:179], v[60:63]
	v_mfma_f32_16x16x32_bf16 v[56:59], v[152:155], v[176:179], v[56:59]
	v_mfma_f32_16x16x32_bf16 v[44:47], v[138:141], v[188:191], v[44:47]
	v_mfma_f32_16x16x32_bf16 v[40:43], v[152:155], v[188:191], v[40:43]
	v_mfma_f32_16x16x32_bf16 v[28:31], v[138:141], v[200:203], v[28:31]
	v_mfma_f32_16x16x32_bf16 v[24:27], v[152:155], v[200:203], v[24:27]
	v_mfma_f32_16x16x32_bf16 v[12:15], v[138:141], v[208:211], v[12:15]
	v_mfma_f32_16x16x32_bf16 v[8:11], v[152:155], v[208:211], v[8:11]
	v_mfma_f32_16x16x32_bf16 v[60:63], v[148:151], v[180:183], v[60:63]
	v_mfma_f32_16x16x32_bf16 v[56:59], v[156:159], v[180:183], v[56:59]
	v_mfma_f32_16x16x32_bf16 v[44:47], v[148:151], v[196:199], v[44:47]
	v_mfma_f32_16x16x32_bf16 v[40:43], v[156:159], v[196:199], v[40:43]
	v_mfma_f32_16x16x32_bf16 v[28:31], v[148:151], v[204:207], v[28:31]
	v_mfma_f32_16x16x32_bf16 v[24:27], v[156:159], v[204:207], v[24:27]
	v_mfma_f32_16x16x32_bf16 v[12:15], v[148:151], v[212:215], v[12:15]
	v_mfma_f32_16x16x32_bf16 v[8:11], v[156:159], v[212:215], v[8:11]
	v_mfma_f32_16x16x32_bf16 v[52:55], v[160:163], v[176:179], v[52:55]
	v_mfma_f32_16x16x32_bf16 v[48:51], v[168:171], v[176:179], v[48:51]
	v_mfma_f32_16x16x32_bf16 v[36:39], v[160:163], v[188:191], v[36:39]
	v_mfma_f32_16x16x32_bf16 v[32:35], v[168:171], v[188:191], v[32:35]
	v_mfma_f32_16x16x32_bf16 v[20:23], v[160:163], v[200:203], v[20:23]
	v_mfma_f32_16x16x32_bf16 v[16:19], v[168:171], v[200:203], v[16:19]
	v_mfma_f32_16x16x32_bf16 v[4:7], v[160:163], v[208:211], v[4:7]
	v_mfma_f32_16x16x32_bf16 v[0:3], v[168:171], v[208:211], v[0:3]
	v_mfma_f32_16x16x32_bf16 v[52:55], v[164:167], v[180:183], v[52:55]
	v_mfma_f32_16x16x32_bf16 v[48:51], v[172:175], v[180:183], v[48:51]
	v_mfma_f32_16x16x32_bf16 v[36:39], v[164:167], v[196:199], v[36:39]
	v_mfma_f32_16x16x32_bf16 v[32:35], v[172:175], v[196:199], v[32:35]
	v_mfma_f32_16x16x32_bf16 v[20:23], v[164:167], v[204:207], v[20:23]
	v_mfma_f32_16x16x32_bf16 v[16:19], v[172:175], v[204:207], v[16:19]
	v_mfma_f32_16x16x32_bf16 v[4:7], v[164:167], v[212:215], v[4:7]
	v_mfma_f32_16x16x32_bf16 v[0:3], v[172:175], v[212:215], v[0:3]
	s_setprio 1
	s_barrier
	s_add_i32 s51, 0, 0x18000
	s_add_i32 s52, 0, 0x1c000
	v_add_u32_e32 v156, s51, v145
	v_add_u32_e32 v172, s52, v145
	ds_read_b128 v[138:141], v156
	ds_read_b128 v[148:151], v156 offset:1024
	ds_read_b128 v[152:155], v156 offset:2048
	ds_read_b128 v[156:159], v156 offset:3072
	ds_read_b128 v[160:163], v172
	ds_read_b128 v[164:167], v172 offset:1024
	ds_read_b128 v[168:171], v172 offset:2048
	ds_read_b128 v[172:175], v172 offset:3072
	s_add_u32 s34, s34, 0x80000
	s_addc_u32 s35, s35, 0
	s_mov_b32 m0, s40
	v_lshl_add_u64 v[222:223], s[34:35], 0, v[128:129]
	ds_read_b128 v[176:179], v147 offset:32768
	ds_read_b128 v[180:183], v147 offset:33792
	ds_read_b128 v[188:191], v147 offset:34816
	ds_read_b128 v[196:199], v147 offset:35840
	ds_read_b128 v[200:203], v147 offset:36864
	ds_read_b128 v[204:207], v147 offset:37888
	ds_read_b128 v[208:211], v147 offset:38912
	ds_read_b128 v[212:215], v147 offset:39936
	global_load_lds_dwordx4 v[222:223], off
	v_lshl_add_u64 v[222:223], s[34:35], 0, v[130:131]
	s_mov_b32 m0, s41
	s_nop 0
	global_load_lds_dwordx4 v[222:223], off
	s_waitcnt vmcnt(8)
	s_waitcnt lgkmcnt(0)
	s_barrier
	s_setprio 0
	s_waitcnt lgkmcnt(0)
	v_mfma_f32_16x16x32_bf16 v[124:127], v[138:141], v[176:179], v[124:127]
	v_mfma_f32_16x16x32_bf16 v[120:123], v[152:155], v[176:179], v[120:123]
	v_mfma_f32_16x16x32_bf16 v[108:111], v[138:141], v[188:191], v[108:111]
	v_mfma_f32_16x16x32_bf16 v[104:107], v[152:155], v[188:191], v[104:107]
	v_mfma_f32_16x16x32_bf16 v[92:95], v[138:141], v[200:203], v[92:95]
	v_mfma_f32_16x16x32_bf16 v[88:91], v[152:155], v[200:203], v[88:91]
	v_mfma_f32_16x16x32_bf16 v[76:79], v[138:141], v[208:211], v[76:79]
	v_mfma_f32_16x16x32_bf16 v[72:75], v[152:155], v[208:211], v[72:75]
	v_mfma_f32_16x16x32_bf16 v[124:127], v[148:151], v[180:183], v[124:127]
	v_mfma_f32_16x16x32_bf16 v[120:123], v[156:159], v[180:183], v[120:123]
	v_mfma_f32_16x16x32_bf16 v[108:111], v[148:151], v[196:199], v[108:111]
	v_mfma_f32_16x16x32_bf16 v[104:107], v[156:159], v[196:199], v[104:107]
	v_mfma_f32_16x16x32_bf16 v[92:95], v[148:151], v[204:207], v[92:95]
	v_mfma_f32_16x16x32_bf16 v[88:91], v[156:159], v[204:207], v[88:91]
	v_mfma_f32_16x16x32_bf16 v[76:79], v[148:151], v[212:215], v[76:79]
	v_mfma_f32_16x16x32_bf16 v[72:75], v[156:159], v[212:215], v[72:75]
	v_mfma_f32_16x16x32_bf16 v[116:119], v[160:163], v[176:179], v[116:119]
	v_mfma_f32_16x16x32_bf16 v[112:115], v[168:171], v[176:179], v[112:115]
	v_mfma_f32_16x16x32_bf16 v[100:103], v[160:163], v[188:191], v[100:103]
	v_mfma_f32_16x16x32_bf16 v[96:99], v[168:171], v[188:191], v[96:99]
	v_mfma_f32_16x16x32_bf16 v[84:87], v[160:163], v[200:203], v[84:87]
	v_mfma_f32_16x16x32_bf16 v[80:83], v[168:171], v[200:203], v[80:83]
	v_mfma_f32_16x16x32_bf16 v[68:71], v[160:163], v[208:211], v[68:71]
	v_mfma_f32_16x16x32_bf16 v[64:67], v[168:171], v[208:211], v[64:67]
	v_mfma_f32_16x16x32_bf16 v[116:119], v[164:167], v[180:183], v[116:119]
	v_mfma_f32_16x16x32_bf16 v[112:115], v[172:175], v[180:183], v[112:115]
	v_mfma_f32_16x16x32_bf16 v[100:103], v[164:167], v[196:199], v[100:103]
	v_mfma_f32_16x16x32_bf16 v[96:99], v[172:175], v[196:199], v[96:99]
	v_mfma_f32_16x16x32_bf16 v[84:87], v[164:167], v[204:207], v[84:87]
	v_mfma_f32_16x16x32_bf16 v[80:83], v[172:175], v[204:207], v[80:83]
	v_mfma_f32_16x16x32_bf16 v[68:71], v[164:167], v[212:215], v[68:71]
	v_mfma_f32_16x16x32_bf16 v[64:67], v[172:175], v[212:215], v[64:67]
	s_setprio 1
	s_barrier
; #define PG8_STAGE(bufoff, gbase, voff) do { _Pragma("unroll") for (int _i = 0; _i < 2; ++_i) \
;         __builtin_amdgcn_global_load_lds((const unsigned*)((const char*)(gbase) + (voff)[_i]), (LAS unsigned*)(lds + (bufoff) + ldsw + _i * 8192), 16, 0, 0); } while (0)
; #define PG8_LDA(dst, b, h) do { _Pragma("unroll") for (int m = 0; m < 4; ++m) _Pragma("unroll") for (int k = 0; k < 2; ++k) dst[m][k] = *(const LAS bf16x8*)(lds + PG8_SA(b, h) + aoff + m * 2048 + k * 1024); } while (0)
; #define PG8_MMA(ai, bj, At, Bt) do { __builtin_amdgcn_s_setprio(1); _Pragma("unroll") for (int m = 0; m < 4; ++m) _Pragma("unroll") for (int n = 0; n < 2; ++n) _Pragma("unroll") for (int k = 0; k < 2; ++k) \
;         acc[ai][bj][m][n] = __builtin_amdgcn_mfma_f32_16x16x32_bf16(Bt[n][k], At[m][k], acc[ai][bj][m][n], 0, 0, 0); __builtin_amdgcn_s_setprio(0); } while (0)
; #define PG8_WAIT_V(n) asm volatile("s_waitcnt vmcnt(" #n ")" ::: "memory")
; #define PG8_WAIT_L(n) asm volatile("s_waitcnt lgkmcnt(" #n ")" ::: "memory")
; #define PG8_BAR __builtin_amdgcn_s_barrier()
; #define PG8_SCHED __builtin_amdgcn_sched_barrier(0)
; template <class Epi, class Sched>
; DI void gemm_phase(LAS unsigned char* lds, const int wv, const int lda, const int ldb, const Sched& S, const Epi& E) {
;     ...
;             PG8_LDA(At, 1, 1); PG8_STAGE(PG8_SB(1, 0), b3, voffB); PG8_STAGE(PG8_SB(1, 1), b3 + hstepB, voffB); PG8_STAGE(PG8_SA(1, 0), a3, voffA);
;             PG8_WAIT_V(8); PG8_WAIT_L(0); PG8_BAR; PG8_MMA(1, 0, At, B0); PG8_MMA(1, 1, At, B1); PG8_BAR; PG8_SCHED;
;         }
;         if (wr == 0) PG8_BAR;
	s_add_i32 s34, s51, s38
	v_lshl_add_u64 v[142:143], v[142:143], 0, s[28:29]
	s_mov_b32 m0, s34
	ds_read_b128 v[176:179], v147 offset:49152
	ds_read_b128 v[180:183], v147 offset:50176
	ds_read_b128 v[188:191], v147 offset:51200
	ds_read_b128 v[196:199], v147 offset:52224
	ds_read_b128 v[200:203], v147 offset:53248
	ds_read_b128 v[204:207], v147 offset:54272
	ds_read_b128 v[208:211], v147 offset:55296
	ds_read_b128 v[212:215], v147 offset:56320
	global_load_lds_dwordx4 v[142:143], off
	s_add_i32 m0, s34, 0x2000
	s_add_u32 s30, s30, 0x80080
	v_lshl_add_u64 v[142:143], v[216:217], 0, s[28:29]
	s_addc_u32 s31, s31, 0
	s_add_i32 s34, s52, s38
	global_load_lds_dwordx4 v[142:143], off
	v_lshl_add_u64 v[142:143], s[30:31], 0, v[184:185]
	s_mov_b32 m0, s34
	s_nop 0
	global_load_lds_dwordx4 v[142:143], off
	v_lshl_add_u64 v[142:143], s[30:31], 0, v[132:133]
	s_add_i32 m0, s34, 0x2000
	s_nop 0
	global_load_lds_dwordx4 v[142:143], off
	v_lshl_add_u64 v[142:143], v[218:219], 0, s[28:29]
	s_mov_b32 m0, s43
	s_nop 0
	global_load_lds_dwordx4 v[142:143], off
	v_lshl_add_u64 v[142:143], v[220:221], 0, s[28:29]
	s_mov_b32 m0, s44
	s_nop 0
	global_load_lds_dwordx4 v[142:143], off
	s_waitcnt vmcnt(8)
	s_waitcnt lgkmcnt(0)
	s_barrier
	s_setprio 0
	s_waitcnt lgkmcnt(0)
	v_mfma_f32_16x16x32_bf16 v[60:63], v[138:141], v[176:179], v[60:63]
	v_mfma_f32_16x16x32_bf16 v[56:59], v[152:155], v[176:179], v[56:59]
	v_mfma_f32_16x16x32_bf16 v[44:47], v[138:141], v[188:191], v[44:47]
	v_mfma_f32_16x16x32_bf16 v[40:43], v[152:155], v[188:191], v[40:43]
	v_mfma_f32_16x16x32_bf16 v[28:31], v[138:141], v[200:203], v[28:31]
	v_mfma_f32_16x16x32_bf16 v[24:27], v[152:155], v[200:203], v[24:27]
	v_mfma_f32_16x16x32_bf16 v[12:15], v[138:141], v[208:211], v[12:15]
	v_mfma_f32_16x16x32_bf16 v[8:11], v[152:155], v[208:211], v[8:11]
	v_mfma_f32_16x16x32_bf16 v[60:63], v[148:151], v[180:183], v[60:63]
	v_mfma_f32_16x16x32_bf16 v[56:59], v[156:159], v[180:183], v[56:59]
	v_mfma_f32_16x16x32_bf16 v[44:47], v[148:151], v[196:199], v[44:47]
	v_mfma_f32_16x16x32_bf16 v[40:43], v[156:159], v[196:199], v[40:43]
	v_mfma_f32_16x16x32_bf16 v[28:31], v[148:151], v[204:207], v[28:31]
	v_mfma_f32_16x16x32_bf16 v[24:27], v[156:159], v[204:207], v[24:27]
	v_mfma_f32_16x16x32_bf16 v[12:15], v[148:151], v[212:215], v[12:15]
	v_mfma_f32_16x16x32_bf16 v[8:11], v[156:159], v[212:215], v[8:11]
	v_mfma_f32_16x16x32_bf16 v[52:55], v[160:163], v[176:179], v[52:55]
	v_mfma_f32_16x16x32_bf16 v[48:51], v[168:171], v[176:179], v[48:51]
	v_mfma_f32_16x16x32_bf16 v[36:39], v[160:163], v[188:191], v[36:39]
	v_mfma_f32_16x16x32_bf16 v[32:35], v[168:171], v[188:191], v[32:35]
	v_mfma_f32_16x16x32_bf16 v[20:23], v[160:163], v[200:203], v[20:23]
	v_mfma_f32_16x16x32_bf16 v[16:19], v[168:171], v[200:203], v[16:19]
	v_mfma_f32_16x16x32_bf16 v[4:7], v[160:163], v[208:211], v[4:7]
	v_mfma_f32_16x16x32_bf16 v[0:3], v[168:171], v[208:211], v[0:3]
	v_mfma_f32_16x16x32_bf16 v[52:55], v[164:167], v[180:183], v[52:55]
	v_mfma_f32_16x16x32_bf16 v[48:51], v[172:175], v[180:183], v[48:51]
	v_mfma_f32_16x16x32_bf16 v[36:39], v[164:167], v[196:199], v[36:39]
	v_mfma_f32_16x16x32_bf16 v[32:35], v[172:175], v[196:199], v[32:35]
	v_mfma_f32_16x16x32_bf16 v[20:23], v[164:167], v[204:207], v[20:23]
	v_mfma_f32_16x16x32_bf16 v[16:19], v[172:175], v[204:207], v[16:19]
	v_mfma_f32_16x16x32_bf16 v[4:7], v[164:167], v[212:215], v[4:7]
	v_mfma_f32_16x16x32_bf16 v[0:3], v[172:175], v[212:215], v[0:3]
	s_setprio 1
	s_barrier
	s_add_i32 s50, s50, 2
	s_add_u32 s26, s26, 0x100
	s_addc_u32 s27, s27, 0
	s_add_u32 s48, s48, 0x100
	s_addc_u32 s49, s49, 0
	s_cmp_gt_u32 s50, 29
	s_cbranch_scc0 .LBB0_1397
	s_and_b64 vcc, exec, s[10:11]
	s_cbranch_vccz .LBB0_1400
	s_barrier

; #define PG8_STAGE(bufoff, gbase, voff) do { _Pragma("unroll") for (int _i = 0; _i < 2; ++_i) \
;         __builtin_amdgcn_global_load_lds((const unsigned*)((const char*)(gbase) + (voff)[_i]), (LAS unsigned*)(lds + (bufoff) + ldsw + _i * 8192), 16, 0, 0); } while (0)
; #define PG8_LDA(dst, b, h) do { _Pragma("unroll") for (int m = 0; m < 4; ++m) _Pragma("unroll") for (int k = 0; k < 2; ++k) dst[m][k] = *(const LAS bf16x8*)(lds + PG8_SA(b, h) + aoff + m * 2048 + k * 1024); } while (0)
; #define PG8_LDB(dst, b, h) do { _Pragma("unroll") for (int n = 0; n < 2; ++n) _Pragma("unroll") for (int k = 0; k < 2; ++k) dst[n][k] = *(const LAS bf16x8*)(lds + PG8_SB(b, h) + boff + n * 2048 + k * 1024); } while (0)
; #define PG8_MMA(ai, bj, At, Bt) do { __builtin_amdgcn_s_setprio(1); _Pragma("unroll") for (int m = 0; m < 4; ++m) _Pragma("unroll") for (int n = 0; n < 2; ++n) _Pragma("unroll") for (int k = 0; k < 2; ++k) \
;         acc[ai][bj][m][n] = __builtin_amdgcn_mfma_f32_16x16x32_bf16(Bt[n][k], At[m][k], acc[ai][bj][m][n], 0, 0, 0); __builtin_amdgcn_s_setprio(0); } while (0)
; #define PG8_WAIT_V(n) asm volatile("s_waitcnt vmcnt(" #n ")" ::: "memory")
; #define PG8_WAIT_L(n) asm volatile("s_waitcnt lgkmcnt(" #n ")" ::: "memory")
; #define PG8_BAR __builtin_amdgcn_s_barrier()
; #define PG8_SCHED __builtin_amdgcn_sched_barrier(0)
; template <class Epi, class Sched>
; DI void gemm_phase(LAS unsigned char* lds, const int wv, const int lda, const int ldb, const Sched& S, const Epi& E) {
;     ...
;             const bool last = (t == nt - 2);
;             const char* a1 = cA + (size_t)(t + 1) * kstep;
;             const char* a2 = last ? nA : cA + (size_t)(t + 2) * kstep; const char* b2 = last ? nB : cB + (size_t)(t + 2) * kstep;
;             const char* a3 = a2 + kstep; const char* b3 = b2 + kstep;
;             PG8_LDB(B0, 0, 0); PG8_LDB(B1, 0, 1); PG8_SCHED; PG8_LDA(At, 0, 0); PG8_STAGE(PG8_SA(1, 1), a1 + hstepA, voffA);
;             PG8_WAIT_V(8); PG8_WAIT_L(0); PG8_BAR; PG8_MMA(0, 0, At, B0); PG8_MMA(0, 1, At, B1); PG8_BAR; PG8_SCHED;
;             PG8_LDA(At, 0, 1); PG8_STAGE(PG8_SB(0, 0), b2, voffB); PG8_STAGE(PG8_SB(0, 1), b2 + hstepB, voffB); PG8_STAGE(PG8_SA(0, 0), a2, voffA);
;             PG8_WAIT_V(8); PG8_WAIT_L(0); PG8_BAR; PG8_MMA(1, 0, At, B0); PG8_MMA(1, 1, At, B1); PG8_BAR; PG8_SCHED;
.LBB0_1477:
	s_add_u32 s36, s34, 0xffe00080
	s_addc_u32 s37, s35, -1
	s_add_i32 s56, 0, 0x10000
	s_cmpk_eq_i32 s55, 0x7c
	s_cselect_b32 s39, s0, s37
	s_cselect_b32 s38, s1, s36
	s_cselect_b32 s37, s11, s54
	s_cselect_b32 s36, s19, s23
	s_add_i32 s58, 0, 0x14000
	v_add_u32_e32 v150, s56, v155
	v_add_u32_e32 v172, s58, v155
	ds_read_b128 v[128:131], v150
	ds_read_b128 v[142:145], v150 offset:1024
	ds_read_b128 v[146:149], v150 offset:2048
	ds_read_b128 v[150:153], v150 offset:3072
	ds_read_b128 v[160:163], v172
	ds_read_b128 v[164:167], v172 offset:1024
	ds_read_b128 v[168:171], v172 offset:2048
	ds_read_b128 v[172:175], v172 offset:3072
	v_lshl_add_u64 v[216:217], s[34:35], 0, v[138:139]
	s_add_i32 m0, s31, 0xc000
	ds_read_b128 v[176:179], v159
	ds_read_b128 v[180:183], v159 offset:1024
	ds_read_b128 v[188:191], v159 offset:2048
	ds_read_b128 v[196:199], v159 offset:3072
	ds_read_b128 v[200:203], v159 offset:4096
	ds_read_b128 v[204:207], v159 offset:5120
	ds_read_b128 v[208:211], v159 offset:6144
	ds_read_b128 v[212:215], v159 offset:7168
	global_load_lds_dwordx4 v[216:217], off
	v_lshl_add_u64 v[216:217], s[34:35], 0, v[140:141]
	s_add_i32 m0, s31, 0xe000
	s_nop 0
	global_load_lds_dwordx4 v[216:217], off
	s_waitcnt vmcnt(8)
	s_waitcnt lgkmcnt(0)
	s_barrier
	s_setprio 0
	s_waitcnt lgkmcnt(0)
	v_mfma_f32_16x16x32_bf16 v[124:127], v[128:131], v[176:179], v[124:127]
	v_mfma_f32_16x16x32_bf16 v[120:123], v[146:149], v[176:179], v[120:123]
	v_mfma_f32_16x16x32_bf16 v[108:111], v[128:131], v[188:191], v[108:111]
	v_mfma_f32_16x16x32_bf16 v[104:107], v[146:149], v[188:191], v[104:107]
	v_mfma_f32_16x16x32_bf16 v[96:99], v[128:131], v[200:203], v[96:99]
	v_mfma_f32_16x16x32_bf16 v[88:91], v[146:149], v[200:203], v[88:91]
	v_mfma_f32_16x16x32_bf16 v[80:83], v[128:131], v[208:211], v[80:83]
	v_mfma_f32_16x16x32_bf16 v[72:75], v[146:149], v[208:211], v[72:75]
	v_mfma_f32_16x16x32_bf16 v[124:127], v[142:145], v[180:183], v[124:127]
	v_mfma_f32_16x16x32_bf16 v[120:123], v[150:153], v[180:183], v[120:123]
	v_mfma_f32_16x16x32_bf16 v[108:111], v[142:145], v[196:199], v[108:111]
	v_mfma_f32_16x16x32_bf16 v[104:107], v[150:153], v[196:199], v[104:107]
	v_mfma_f32_16x16x32_bf16 v[96:99], v[142:145], v[204:207], v[96:99]
	v_mfma_f32_16x16x32_bf16 v[88:91], v[150:153], v[204:207], v[88:91]
	v_mfma_f32_16x16x32_bf16 v[80:83], v[142:145], v[212:215], v[80:83]
	v_mfma_f32_16x16x32_bf16 v[72:75], v[150:153], v[212:215], v[72:75]
	v_mfma_f32_16x16x32_bf16 v[116:119], v[160:163], v[176:179], v[116:119]
	v_mfma_f32_16x16x32_bf16 v[112:115], v[168:171], v[176:179], v[112:115]
	v_mfma_f32_16x16x32_bf16 v[100:103], v[160:163], v[188:191], v[100:103]
	v_mfma_f32_16x16x32_bf16 v[92:95], v[168:171], v[188:191], v[92:95]
	v_mfma_f32_16x16x32_bf16 v[84:87], v[160:163], v[200:203], v[84:87]
	v_mfma_f32_16x16x32_bf16 v[76:79], v[168:171], v[200:203], v[76:79]
	v_mfma_f32_16x16x32_bf16 v[68:71], v[160:163], v[208:211], v[68:71]
	v_mfma_f32_16x16x32_bf16 v[64:67], v[168:171], v[208:211], v[64:67]
	v_mfma_f32_16x16x32_bf16 v[116:119], v[164:167], v[180:183], v[116:119]
	v_mfma_f32_16x16x32_bf16 v[112:115], v[172:175], v[180:183], v[112:115]
	v_mfma_f32_16x16x32_bf16 v[100:103], v[164:167], v[196:199], v[100:103]
	v_mfma_f32_16x16x32_bf16 v[92:95], v[172:175], v[196:199], v[92:95]
	v_mfma_f32_16x16x32_bf16 v[84:87], v[164:167], v[204:207], v[84:87]
	v_mfma_f32_16x16x32_bf16 v[76:79], v[172:175], v[204:207], v[76:79]
	v_mfma_f32_16x16x32_bf16 v[68:71], v[164:167], v[212:215], v[68:71]
	v_mfma_f32_16x16x32_bf16 v[64:67], v[172:175], v[212:215], v[64:67]
	s_setprio 1
	s_barrier
	s_add_i32 s56, s56, s43
	v_lshl_add_u64 v[216:217], s[36:37], 0, v[184:185]
	s_mov_b32 m0, s56
	ds_read_b128 v[176:179], v159 offset:16384
	ds_read_b128 v[180:183], v159 offset:17408
	ds_read_b128 v[188:191], v159 offset:18432
	ds_read_b128 v[196:199], v159 offset:19456
	ds_read_b128 v[200:203], v159 offset:20480
	ds_read_b128 v[204:207], v159 offset:21504
	ds_read_b128 v[208:211], v159 offset:22528
	ds_read_b128 v[212:215], v159 offset:23552
	global_load_lds_dwordx4 v[216:217], off
	s_add_i32 m0, s56, 0x2000
	s_add_u32 s56, s36, 0x200000
	v_lshl_add_u64 v[218:219], s[36:37], 0, v[136:137]
	s_addc_u32 s57, s37, 0
	s_add_i32 s58, s58, s43
	global_load_lds_dwordx4 v[218:219], off
	v_lshl_add_u64 v[220:221], s[56:57], 0, v[184:185]
	s_mov_b32 m0, s58
	v_lshl_add_u64 v[222:223], s[38:39], 0, v[134:135]
	global_load_lds_dwordx4 v[220:221], off
	v_lshl_add_u64 v[220:221], s[56:57], 0, v[136:137]
	s_add_i32 m0, s58, 0x2000
	s_nop 0
	global_load_lds_dwordx4 v[220:221], off
	v_lshl_add_u64 v[220:221], s[38:39], 0, v[132:133]
	s_mov_b32 m0, s31
	s_nop 0
	global_load_lds_dwordx4 v[220:221], off
	s_mov_b32 m0, s44
	s_nop 0
	global_load_lds_dwordx4 v[222:223], off
	s_waitcnt vmcnt(8)
	s_waitcnt lgkmcnt(0)
	s_barrier
; #define PG8_STAGE(bufoff, gbase, voff) do { _Pragma("unroll") for (int _i = 0; _i < 2; ++_i) \
;         __builtin_amdgcn_global_load_lds((const unsigned*)((const char*)(gbase) + (voff)[_i]), (LAS unsigned*)(lds + (bufoff) + ldsw + _i * 8192), 16, 0, 0); } while (0)
; #define PG8_LDA(dst, b, h) do { _Pragma("unroll") for (int m = 0; m < 4; ++m) _Pragma("unroll") for (int k = 0; k < 2; ++k) dst[m][k] = *(const LAS bf16x8*)(lds + PG8_SA(b, h) + aoff + m * 2048 + k * 1024); } while (0)
; #define PG8_LDB(dst, b, h) do { _Pragma("unroll") for (int n = 0; n < 2; ++n) _Pragma("unroll") for (int k = 0; k < 2; ++k) dst[n][k] = *(const LAS bf16x8*)(lds + PG8_SB(b, h) + boff + n * 2048 + k * 1024); } while (0)
; #define PG8_MMA(ai, bj, At, Bt) do { __builtin_amdgcn_s_setprio(1); _Pragma("unroll") for (int m = 0; m < 4; ++m) _Pragma("unroll") for (int n = 0; n < 2; ++n) _Pragma("unroll") for (int k = 0; k < 2; ++k) \
;         acc[ai][bj][m][n] = __builtin_amdgcn_mfma_f32_16x16x32_bf16(Bt[n][k], At[m][k], acc[ai][bj][m][n], 0, 0, 0); __builtin_amdgcn_s_setprio(0); } while (0)
; #define PG8_WAIT_V(n) asm volatile("s_waitcnt vmcnt(" #n ")" ::: "memory")
; #define PG8_WAIT_L(n) asm volatile("s_waitcnt lgkmcnt(" #n ")" ::: "memory")
; #define PG8_BAR __builtin_amdgcn_s_barrier()
; #define PG8_SCHED __builtin_amdgcn_sched_barrier(0)
; template <class Epi, class Sched>
; DI void gemm_phase(LAS unsigned char* lds, const int wv, const int lda, const int ldb, const Sched& S, const Epi& E) {
;     ...
;             PG8_WAIT_V(8); PG8_WAIT_L(0); PG8_BAR; PG8_MMA(1, 0, At, B0); PG8_MMA(1, 1, At, B1); PG8_BAR; PG8_SCHED;
;             PG8_LDB(B0, 1, 0); PG8_LDB(B1, 1, 1); PG8_SCHED; PG8_LDA(At, 1, 0); PG8_STAGE(PG8_SA(0, 1), a2 + hstepA, voffA);
;             PG8_WAIT_V(8); PG8_WAIT_L(0); PG8_BAR; PG8_MMA(0, 0, At, B0); PG8_MMA(0, 1, At, B1); PG8_BAR; PG8_SCHED;
	s_setprio 0
	s_waitcnt lgkmcnt(0)
	v_mfma_f32_16x16x32_bf16 v[60:63], v[128:131], v[176:179], v[60:63]
	v_mfma_f32_16x16x32_bf16 v[56:59], v[146:149], v[176:179], v[56:59]
	v_mfma_f32_16x16x32_bf16 v[48:51], v[128:131], v[188:191], v[48:51]
	v_mfma_f32_16x16x32_bf16 v[40:43], v[146:149], v[188:191], v[40:43]
	v_mfma_f32_16x16x32_bf16 v[32:35], v[128:131], v[200:203], v[32:35]
	v_mfma_f32_16x16x32_bf16 v[24:27], v[146:149], v[200:203], v[24:27]
	v_mfma_f32_16x16x32_bf16 v[16:19], v[128:131], v[208:211], v[16:19]
	v_mfma_f32_16x16x32_bf16 v[8:11], v[146:149], v[208:211], v[8:11]
	v_mfma_f32_16x16x32_bf16 v[60:63], v[142:145], v[180:183], v[60:63]
	v_mfma_f32_16x16x32_bf16 v[56:59], v[150:153], v[180:183], v[56:59]
	v_mfma_f32_16x16x32_bf16 v[48:51], v[142:145], v[196:199], v[48:51]
	v_mfma_f32_16x16x32_bf16 v[40:43], v[150:153], v[196:199], v[40:43]
	v_mfma_f32_16x16x32_bf16 v[32:35], v[142:145], v[204:207], v[32:35]
	v_mfma_f32_16x16x32_bf16 v[24:27], v[150:153], v[204:207], v[24:27]
	v_mfma_f32_16x16x32_bf16 v[16:19], v[142:145], v[212:215], v[16:19]
	v_mfma_f32_16x16x32_bf16 v[8:11], v[150:153], v[212:215], v[8:11]
	v_mfma_f32_16x16x32_bf16 v[52:55], v[160:163], v[176:179], v[52:55]
	v_mfma_f32_16x16x32_bf16 v[44:47], v[168:171], v[176:179], v[44:47]
	v_mfma_f32_16x16x32_bf16 v[36:39], v[160:163], v[188:191], v[36:39]
	v_mfma_f32_16x16x32_bf16 v[28:31], v[168:171], v[188:191], v[28:31]
	v_mfma_f32_16x16x32_bf16 v[20:23], v[160:163], v[200:203], v[20:23]
	v_mfma_f32_16x16x32_bf16 v[12:15], v[168:171], v[200:203], v[12:15]
	v_mfma_f32_16x16x32_bf16 v[4:7], v[160:163], v[208:211], v[4:7]
	v_mfma_f32_16x16x32_bf16 v[0:3], v[168:171], v[208:211], v[0:3]
	v_mfma_f32_16x16x32_bf16 v[52:55], v[164:167], v[180:183], v[52:55]
	v_mfma_f32_16x16x32_bf16 v[44:47], v[172:175], v[180:183], v[44:47]
	v_mfma_f32_16x16x32_bf16 v[36:39], v[164:167], v[196:199], v[36:39]
	v_mfma_f32_16x16x32_bf16 v[28:31], v[172:175], v[196:199], v[28:31]
	v_mfma_f32_16x16x32_bf16 v[20:23], v[164:167], v[204:207], v[20:23]
	v_mfma_f32_16x16x32_bf16 v[12:15], v[172:175], v[204:207], v[12:15]
	v_mfma_f32_16x16x32_bf16 v[4:7], v[164:167], v[212:215], v[4:7]
	v_mfma_f32_16x16x32_bf16 v[0:3], v[172:175], v[212:215], v[0:3]
	s_setprio 1
	s_barrier
	s_add_i32 s56, 0, 0x18000
	s_add_i32 s57, 0, 0x1c000
	v_add_u32_e32 v150, s56, v155
	v_add_u32_e32 v172, s57, v155
	ds_read_b128 v[128:131], v150
	ds_read_b128 v[142:145], v150 offset:1024
	ds_read_b128 v[146:149], v150 offset:2048
	ds_read_b128 v[150:153], v150 offset:3072
	ds_read_b128 v[160:163], v172
	ds_read_b128 v[164:167], v172 offset:1024
	ds_read_b128 v[168:171], v172 offset:2048
	ds_read_b128 v[172:175], v172 offset:3072
	s_add_u32 s38, s38, 0x200000
	s_addc_u32 s39, s39, 0
	s_mov_b32 m0, s45
	v_lshl_add_u64 v[234:235], s[38:39], 0, v[132:133]
	ds_read_b128 v[176:179], v159 offset:32768
	ds_read_b128 v[180:183], v159 offset:33792
	ds_read_b128 v[188:191], v159 offset:34816
	ds_read_b128 v[196:199], v159 offset:35840
	ds_read_b128 v[200:203], v159 offset:36864
	ds_read_b128 v[204:207], v159 offset:37888
	ds_read_b128 v[208:211], v159 offset:38912
	ds_read_b128 v[212:215], v159 offset:39936
	global_load_lds_dwordx4 v[234:235], off
	v_lshl_add_u64 v[234:235], s[38:39], 0, v[134:135]
	s_mov_b32 m0, s46
	s_nop 0
	global_load_lds_dwordx4 v[234:235], off
	s_waitcnt vmcnt(8)
	s_waitcnt lgkmcnt(0)
	s_barrier
	s_setprio 0
	s_waitcnt lgkmcnt(0)
	v_mfma_f32_16x16x32_bf16 v[124:127], v[128:131], v[176:179], v[124:127]
	v_mfma_f32_16x16x32_bf16 v[120:123], v[146:149], v[176:179], v[120:123]
	v_mfma_f32_16x16x32_bf16 v[108:111], v[128:131], v[188:191], v[108:111]
	v_mfma_f32_16x16x32_bf16 v[104:107], v[146:149], v[188:191], v[104:107]
	v_mfma_f32_16x16x32_bf16 v[96:99], v[128:131], v[200:203], v[96:99]
	v_mfma_f32_16x16x32_bf16 v[88:91], v[146:149], v[200:203], v[88:91]
	v_mfma_f32_16x16x32_bf16 v[80:83], v[128:131], v[208:211], v[80:83]
	v_mfma_f32_16x16x32_bf16 v[72:75], v[146:149], v[208:211], v[72:75]
	v_mfma_f32_16x16x32_bf16 v[124:127], v[142:145], v[180:183], v[124:127]
	v_mfma_f32_16x16x32_bf16 v[120:123], v[150:153], v[180:183], v[120:123]
	v_mfma_f32_16x16x32_bf16 v[108:111], v[142:145], v[196:199], v[108:111]
	v_mfma_f32_16x16x32_bf16 v[104:107], v[150:153], v[196:199], v[104:107]
	v_mfma_f32_16x16x32_bf16 v[96:99], v[142:145], v[204:207], v[96:99]
	v_mfma_f32_16x16x32_bf16 v[88:91], v[150:153], v[204:207], v[88:91]
	v_mfma_f32_16x16x32_bf16 v[80:83], v[142:145], v[212:215], v[80:83]
	v_mfma_f32_16x16x32_bf16 v[72:75], v[150:153], v[212:215], v[72:75]
	v_mfma_f32_16x16x32_bf16 v[116:119], v[160:163], v[176:179], v[116:119]
	v_mfma_f32_16x16x32_bf16 v[112:115], v[168:171], v[176:179], v[112:115]
	v_mfma_f32_16x16x32_bf16 v[100:103], v[160:163], v[188:191], v[100:103]
	v_mfma_f32_16x16x32_bf16 v[92:95], v[168:171], v[188:191], v[92:95]
	v_mfma_f32_16x16x32_bf16 v[84:87], v[160:163], v[200:203], v[84:87]
	v_mfma_f32_16x16x32_bf16 v[76:79], v[168:171], v[200:203], v[76:79]
	v_mfma_f32_16x16x32_bf16 v[68:71], v[160:163], v[208:211], v[68:71]
	v_mfma_f32_16x16x32_bf16 v[64:67], v[168:171], v[208:211], v[64:67]
	v_mfma_f32_16x16x32_bf16 v[116:119], v[164:167], v[180:183], v[116:119]
	v_mfma_f32_16x16x32_bf16 v[112:115], v[172:175], v[180:183], v[112:115]
	v_mfma_f32_16x16x32_bf16 v[100:103], v[164:167], v[196:199], v[100:103]
	v_mfma_f32_16x16x32_bf16 v[92:95], v[172:175], v[196:199], v[92:95]
	v_mfma_f32_16x16x32_bf16 v[84:87], v[164:167], v[204:207], v[84:87]
	v_mfma_f32_16x16x32_bf16 v[76:79], v[172:175], v[204:207], v[76:79]
	v_mfma_f32_16x16x32_bf16 v[68:71], v[164:167], v[212:215], v[68:71]
	v_mfma_f32_16x16x32_bf16 v[64:67], v[172:175], v[212:215], v[64:67]
	s_setprio 1
	s_barrier
; #define PG8_STAGE(bufoff, gbase, voff) do { _Pragma("unroll") for (int _i = 0; _i < 2; ++_i) \
;         __builtin_amdgcn_global_load_lds((const unsigned*)((const char*)(gbase) + (voff)[_i]), (LAS unsigned*)(lds + (bufoff) + ldsw + _i * 8192), 16, 0, 0); } while (0)
; #define PG8_LDA(dst, b, h) do { _Pragma("unroll") for (int m = 0; m < 4; ++m) _Pragma("unroll") for (int k = 0; k < 2; ++k) dst[m][k] = *(const LAS bf16x8*)(lds + PG8_SA(b, h) + aoff + m * 2048 + k * 1024); } while (0)
; #define PG8_MMA(ai, bj, At, Bt) do { __builtin_amdgcn_s_setprio(1); _Pragma("unroll") for (int m = 0; m < 4; ++m) _Pragma("unroll") for (int n = 0; n < 2; ++n) _Pragma("unroll") for (int k = 0; k < 2; ++k) \
;         acc[ai][bj][m][n] = __builtin_amdgcn_mfma_f32_16x16x32_bf16(Bt[n][k], At[m][k], acc[ai][bj][m][n], 0, 0, 0); __builtin_amdgcn_s_setprio(0); } while (0)
; #define PG8_WAIT_V(n) asm volatile("s_waitcnt vmcnt(" #n ")" ::: "memory")
; #define PG8_WAIT_L(n) asm volatile("s_waitcnt lgkmcnt(" #n ")" ::: "memory")
; #define PG8_BAR __builtin_amdgcn_s_barrier()
; #define PG8_SCHED __builtin_amdgcn_sched_barrier(0)
; template <class Epi, class Sched>
; DI void gemm_phase(LAS unsigned char* lds, const int wv, const int lda, const int ldb, const Sched& S, const Epi& E) {
;     ...
;             PG8_LDA(At, 1, 1); PG8_STAGE(PG8_SB(1, 0), b3, voffB); PG8_STAGE(PG8_SB(1, 1), b3 + hstepB, voffB); PG8_STAGE(PG8_SA(1, 0), a3, voffA);
;             PG8_WAIT_V(8); PG8_WAIT_L(0); PG8_BAR; PG8_MMA(1, 0, At, B0); PG8_MMA(1, 1, At, B1); PG8_BAR; PG8_SCHED;
;         }
;         if (wr == 0) PG8_BAR;
	s_add_i32 s38, s56, s43
	v_lshl_add_u64 v[216:217], v[216:217], 0, s[28:29]
	s_mov_b32 m0, s38
	ds_read_b128 v[176:179], v159 offset:49152
	ds_read_b128 v[180:183], v159 offset:50176
	ds_read_b128 v[188:191], v159 offset:51200
	ds_read_b128 v[196:199], v159 offset:52224
	ds_read_b128 v[200:203], v159 offset:53248
	ds_read_b128 v[204:207], v159 offset:54272
	ds_read_b128 v[208:211], v159 offset:55296
	ds_read_b128 v[212:215], v159 offset:56320
	global_load_lds_dwordx4 v[216:217], off
	s_add_i32 m0, s38, 0x2000
	s_add_u32 s36, s36, 0x200080
	v_lshl_add_u64 v[216:217], v[218:219], 0, s[28:29]
	s_addc_u32 s37, s37, 0
	s_add_i32 s38, s57, s43
	global_load_lds_dwordx4 v[216:217], off
	v_lshl_add_u64 v[216:217], s[36:37], 0, v[184:185]
	s_mov_b32 m0, s38
	s_nop 0
	global_load_lds_dwordx4 v[216:217], off
	v_lshl_add_u64 v[216:217], s[36:37], 0, v[136:137]
	s_add_i32 m0, s38, 0x2000
	s_nop 0
	global_load_lds_dwordx4 v[216:217], off
	v_lshl_add_u64 v[216:217], v[220:221], 0, s[28:29]
	s_mov_b32 m0, s47
	s_nop 0
	global_load_lds_dwordx4 v[216:217], off
	v_lshl_add_u64 v[216:217], v[222:223], 0, s[28:29]
	s_mov_b32 m0, s48
	s_nop 0
	global_load_lds_dwordx4 v[216:217], off
	s_waitcnt vmcnt(8)
	s_waitcnt lgkmcnt(0)
	s_barrier
	s_setprio 0
	s_waitcnt lgkmcnt(0)
	v_mfma_f32_16x16x32_bf16 v[60:63], v[128:131], v[176:179], v[60:63]
	v_mfma_f32_16x16x32_bf16 v[56:59], v[146:149], v[176:179], v[56:59]
	v_mfma_f32_16x16x32_bf16 v[48:51], v[128:131], v[188:191], v[48:51]
	v_mfma_f32_16x16x32_bf16 v[40:43], v[146:149], v[188:191], v[40:43]
	v_mfma_f32_16x16x32_bf16 v[32:35], v[128:131], v[200:203], v[32:35]
	v_mfma_f32_16x16x32_bf16 v[24:27], v[146:149], v[200:203], v[24:27]
	v_mfma_f32_16x16x32_bf16 v[16:19], v[128:131], v[208:211], v[16:19]
	v_mfma_f32_16x16x32_bf16 v[8:11], v[146:149], v[208:211], v[8:11]
	v_mfma_f32_16x16x32_bf16 v[60:63], v[142:145], v[180:183], v[60:63]
	v_mfma_f32_16x16x32_bf16 v[56:59], v[150:153], v[180:183], v[56:59]
	v_mfma_f32_16x16x32_bf16 v[48:51], v[142:145], v[196:199], v[48:51]
	v_mfma_f32_16x16x32_bf16 v[40:43], v[150:153], v[196:199], v[40:43]
	v_mfma_f32_16x16x32_bf16 v[32:35], v[142:145], v[204:207], v[32:35]
	v_mfma_f32_16x16x32_bf16 v[24:27], v[150:153], v[204:207], v[24:27]
	v_mfma_f32_16x16x32_bf16 v[16:19], v[142:145], v[212:215], v[16:19]
	v_mfma_f32_16x16x32_bf16 v[8:11], v[150:153], v[212:215], v[8:11]
	v_mfma_f32_16x16x32_bf16 v[52:55], v[160:163], v[176:179], v[52:55]
	v_mfma_f32_16x16x32_bf16 v[44:47], v[168:171], v[176:179], v[44:47]
	v_mfma_f32_16x16x32_bf16 v[36:39], v[160:163], v[188:191], v[36:39]
	v_mfma_f32_16x16x32_bf16 v[28:31], v[168:171], v[188:191], v[28:31]
	v_mfma_f32_16x16x32_bf16 v[20:23], v[160:163], v[200:203], v[20:23]
	v_mfma_f32_16x16x32_bf16 v[12:15], v[168:171], v[200:203], v[12:15]
	v_mfma_f32_16x16x32_bf16 v[4:7], v[160:163], v[208:211], v[4:7]
	v_mfma_f32_16x16x32_bf16 v[0:3], v[168:171], v[208:211], v[0:3]
	v_mfma_f32_16x16x32_bf16 v[52:55], v[164:167], v[180:183], v[52:55]
	v_mfma_f32_16x16x32_bf16 v[44:47], v[172:175], v[180:183], v[44:47]
	v_mfma_f32_16x16x32_bf16 v[36:39], v[164:167], v[196:199], v[36:39]
	v_mfma_f32_16x16x32_bf16 v[28:31], v[172:175], v[196:199], v[28:31]
	v_mfma_f32_16x16x32_bf16 v[20:23], v[164:167], v[204:207], v[20:23]
	v_mfma_f32_16x16x32_bf16 v[12:15], v[172:175], v[204:207], v[12:15]
	v_mfma_f32_16x16x32_bf16 v[4:7], v[164:167], v[212:215], v[4:7]
	v_mfma_f32_16x16x32_bf16 v[0:3], v[172:175], v[212:215], v[0:3]
	s_setprio 1
	s_barrier
	s_add_i32 s55, s55, 2
	s_add_u32 s34, s34, 0x100
	s_addc_u32 s35, s35, 0
	s_add_u32 s23, s23, 0x100
	s_addc_u32 s54, s54, 0
	s_cmpk_gt_u32 s55, 0x7d
	s_cbranch_scc0 .LBB0_1477
	s_and_b64 vcc, exec, s[14:15]
	s_cbranch_vccz .LBB0_1480
	s_barrier
